# FFN-gate epilogue: next tile's tap table staged at the end of this tile's epilogue (no tap wait, no drain of the next tile's operand prefetch)
# speedup vs baseline: 1.0009x; 1.0009x over previous
; __global__ void __launch_bounds__(512, 2) fwd_megakernel(Args a_in) {
;     ...
;     for (int ph = ph_lo; ph < ph_hi; ++ph) {
;         const __attribute__((address_space(4))) Args* apz = (const __attribute__((address_space(4))) Args*)__builtin_amdgcn_kernarg_segment_ptr();
;         asm volatile("" : "+s"(apz));
;         const __attribute__((address_space(4))) Args& a = *apz;
;         int tid = threadIdx.x; asm volatile("" : "+v"(tid));
;         const int wave = __builtin_amdgcn_readfirstlane(tid >> 6);
;     ...
;         int bid = blockIdx.x; asm volatile("" : "+s"(bid));
;         const int G = gridDim.x, gw = bid * 8 + wave, NGW = G * 8, gtid = bid * 512 + tid, NTH = G * 512;
;         unsigned char* ws = a.ws;
;         float* mods = (float*)(ws + WS_MODS);
;         float* XC = (float*)(ws + WS_XC);
;         bf16_t* H = (bf16_t*)(ws + WS_H);
;         bf16_t* U = (bf16_t*)(ws + WS_U);
;         bf16_t* RC = (bf16_t*)(ws + WS_RC);
;         bf16_t* SIDE = (bf16_t*)(ws + WS_SIDE);
;         int kind = -1, layer = 0, slot = 0;
;         if (ph == 0) kind = 0; else if (ph == 41) kind = 8;
;         else { layer = (ph - 1) / 10; slot = (ph - 1) % 10;
;             kind = (slot == 0 || slot == 5) ? 1 : (slot == 1 || slot == 6) ? 2 : slot == 2 ? 3 : slot == 3 ? 4 : (slot == 4 || slot == 9) ? 5 : slot == 7 ? 6 : 7; }
.LBB0_9:
	s_mov_b64 s[62:63], s[94:95]
	s_mov_b32 s101, 0
	v_mov_b32_e32 v196, v201
	s_mov_b32 s96, s2
	s_waitcnt lgkmcnt(0)
	s_load_dwordx2 s[54:55], s[62:63], 0xc0
	v_readfirstlane_b32 s1, v196
	s_cmp_lt_i32 s20, 41
	s_cbranch_scc1 .LBB0_14
	s_cmp_eq_u32 s20, 41
	s_mov_b64 s[4:5], -1
	s_cbranch_scc0 .LBB0_12
	s_mov_b64 s[4:5], 0

; #define PG8_STAGE(bufoff, gbase, voff) do { _Pragma("unroll") for (int _i = 0; _i < 2; ++_i) \
;         __builtin_amdgcn_global_load_lds((const unsigned*)((const char*)(gbase) + (voff)[_i]), (LAS unsigned*)(lds + (bufoff) + ldsw + _i * 8192), 16, 0, 0); } while (0)
; #define PG8_LDA(dst, b, h) do { _Pragma("unroll") for (int m = 0; m < 4; ++m) _Pragma("unroll") for (int k = 0; k < 2; ++k) dst[m][k] = *(const LAS bf16x8*)(lds + PG8_SA(b, h) + aoff + m * 2048 + k * 1024); } while (0)
; #define PG8_LDB(dst, b, h) do { _Pragma("unroll") for (int n = 0; n < 2; ++n) _Pragma("unroll") for (int k = 0; k < 2; ++k) dst[n][k] = *(const LAS bf16x8*)(lds + PG8_SB(b, h) + boff + n * 2048 + k * 1024); } while (0)
; #define PG8_WAIT_V(n) asm volatile("s_waitcnt vmcnt(" #n ")" ::: "memory")
; #define PG8_WAIT_L(n) asm volatile("s_waitcnt lgkmcnt(" #n ")" ::: "memory")
; template <class Epi>
; __device__ __forceinline__ void gemm_phase(ldsp lds, const Gemm g, const StaticOrder& S, const Epi& E, const int tid) {
;     ...
;         for (int t = 0; t < nt; t += 2) {
;             const bool last = (t == nt - 2);
;             const char* a1 = cA + (size_t)(t + 1) * kstep;
;             const char* a2 = last ? nA : cA + (size_t)(t + 2) * kstep; const char* b2 = last ? nB : cB + (size_t)(t + 2) * kstep;
;             const char* a3 = a2 + kstep; const char* b3 = b2 + kstep;
;             PG8_LDB(B0, 0, 0); PG8_LDB(B1, 0, 1); PG8_SCHED; PG8_LDA(At, 0, 0); PG8_STAGE(PG8_SA(1, 1), a1 + hstepA, voffA);
;             PG8_WAIT_V(8); PG8_WAIT_L(0); PG8_BAR; PG8_MMA(0, 0, At, B0); PG8_MMA(0, 1, At, B1); PG8_BAR; PG8_SCHED;
;             PG8_LDA(At, 0, 1); PG8_STAGE(PG8_SB(0, 0), b2, voffB); PG8_STAGE(PG8_SB(0, 1), b2 + hstepB, voffB); PG8_STAGE(PG8_SA(0, 0), a2, voffA);
;             PG8_WAIT_V(8); PG8_WAIT_L(0); PG8_BAR; PG8_MMA(1, 0, At, B0); PG8_MMA(1, 1, At, B1); PG8_BAR; PG8_SCHED;
;             PG8_LDB(B0, 1, 0); PG8_LDB(B1, 1, 1); PG8_SCHED; PG8_LDA(At, 1, 0); PG8_STAGE(PG8_SA(0, 1), a2 + hstepA, voffA);
;             PG8_WAIT_V(8); PG8_WAIT_L(0); PG8_BAR; PG8_MMA(0, 0, At, B0); PG8_MMA(0, 1, At, B1); PG8_BAR; PG8_SCHED;
;             PG8_LDA(At, 1, 1); PG8_STAGE(PG8_SB(1, 0), b3, voffB); PG8_STAGE(PG8_SB(1, 1), b3 + hstepB, voffB); PG8_STAGE(PG8_SA(1, 0), a3, voffA);
;             PG8_WAIT_V(8); PG8_WAIT_L(0); PG8_BAR; PG8_MMA(1, 0, At, B0); PG8_MMA(1, 1, At, B1); PG8_BAR; PG8_SCHED;
.LBB0_1043:
	s_add_u32 s10, s6, 0xfffc0080
	s_addc_u32 s11, s7, -1
	s_add_i32 s29, 0, 0x10000
	s_cmp_eq_u32 s27, 12
	s_cselect_b32 s13, s0, s11
	s_cselect_b32 s12, s1, s10
	v_add_u32_e32 v96, s29, v184
	s_cselect_b32 s11, s3, s23
	s_cselect_b32 s10, s9, s22
	s_add_i32 s38, 0, 0x14000
	ds_read_b128 v[130:133], v96
	ds_read_b128 v[134:137], v96 offset:1024
	ds_read_b128 v[138:141], v96 offset:2048
	ds_read_b128 v[142:145], v96 offset:3072
	v_add_u32_e32 v96, s38, v184
	ds_read_b128 v[158:161], v96
	ds_read_b128 v[162:165], v96 offset:1024
	ds_read_b128 v[166:169], v96 offset:2048
	ds_read_b128 v[170:173], v96 offset:3072
	v_lshl_add_u64 v[194:195], s[6:7], 0, v[154:155]
	s_add_i32 m0, s85, 0xc000
	ds_read_b128 v[174:177], v185
	ds_read_b128 v[178:181], v185 offset:1024
	ds_read_b128 v[186:189], v185 offset:2048
	ds_read_b128 v[190:193], v185 offset:3072
	ds_read_b128 v[226:229], v185 offset:4096
	ds_read_b128 v[230:233], v185 offset:5120
	ds_read_b128 v[234:237], v185 offset:6144
	ds_read_b128 v[238:241], v185 offset:7168
	global_load_lds_dwordx4 v[194:195], off
	v_lshl_add_u64 v[194:195], s[6:7], 0, v[156:157]
	s_add_i32 m0, s85, 0xe000
	s_nop 0
	global_load_lds_dwordx4 v[194:195], off
	s_waitcnt vmcnt(8)
	s_waitcnt lgkmcnt(0)
	s_barrier
	s_setprio 1
	s_waitcnt lgkmcnt(0)
	v_mfma_f32_16x16x32_bf16 v[110:113], v[130:133], v[174:177], v[110:113]
	v_mfma_f32_16x16x32_bf16 v[76:79], v[138:141], v[174:177], v[76:79]
	v_mfma_f32_16x16x32_bf16 v[126:129], v[130:133], v[186:189], v[126:129]
	v_mfma_f32_16x16x32_bf16 v[92:95], v[138:141], v[186:189], v[92:95]
	v_mfma_f32_16x16x32_bf16 v[122:125], v[130:133], v[226:229], v[122:125]
	v_mfma_f32_16x16x32_bf16 v[88:91], v[138:141], v[226:229], v[88:91]
	v_mfma_f32_16x16x32_bf16 v[106:109], v[130:133], v[234:237], v[106:109]
	v_mfma_f32_16x16x32_bf16 v[72:75], v[138:141], v[234:237], v[72:75]
	v_mfma_f32_16x16x32_bf16 v[110:113], v[134:137], v[178:181], v[110:113]
	v_mfma_f32_16x16x32_bf16 v[76:79], v[142:145], v[178:181], v[76:79]
	v_mfma_f32_16x16x32_bf16 v[126:129], v[134:137], v[190:193], v[126:129]
	v_mfma_f32_16x16x32_bf16 v[92:95], v[142:145], v[190:193], v[92:95]
	v_mfma_f32_16x16x32_bf16 v[122:125], v[134:137], v[230:233], v[122:125]
	v_mfma_f32_16x16x32_bf16 v[88:91], v[142:145], v[230:233], v[88:91]
	v_mfma_f32_16x16x32_bf16 v[106:109], v[134:137], v[238:241], v[106:109]
	v_mfma_f32_16x16x32_bf16 v[72:75], v[142:145], v[238:241], v[72:75]
	s_setprio 0
	s_setprio 1
	v_mfma_f32_16x16x32_bf16 v[102:105], v[158:161], v[174:177], v[102:105]
	v_mfma_f32_16x16x32_bf16 v[64:67], v[166:169], v[174:177], v[64:67]
	v_mfma_f32_16x16x32_bf16 v[118:121], v[158:161], v[186:189], v[118:121]
	v_mfma_f32_16x16x32_bf16 v[84:87], v[166:169], v[186:189], v[84:87]
	v_mfma_f32_16x16x32_bf16 v[114:117], v[158:161], v[226:229], v[114:117]
	v_mfma_f32_16x16x32_bf16 v[80:83], v[166:169], v[226:229], v[80:83]
	v_mfma_f32_16x16x32_bf16 v[98:101], v[158:161], v[234:237], v[98:101]
	v_mfma_f32_16x16x32_bf16 v[68:71], v[166:169], v[234:237], v[68:71]
	v_mfma_f32_16x16x32_bf16 v[102:105], v[162:165], v[178:181], v[102:105]
	v_mfma_f32_16x16x32_bf16 v[64:67], v[170:173], v[178:181], v[64:67]
	v_mfma_f32_16x16x32_bf16 v[118:121], v[162:165], v[190:193], v[118:121]
	v_mfma_f32_16x16x32_bf16 v[84:87], v[170:173], v[190:193], v[84:87]
	v_mfma_f32_16x16x32_bf16 v[114:117], v[162:165], v[230:233], v[114:117]
	v_mfma_f32_16x16x32_bf16 v[80:83], v[170:173], v[230:233], v[80:83]
	v_mfma_f32_16x16x32_bf16 v[98:101], v[162:165], v[238:241], v[98:101]
	v_mfma_f32_16x16x32_bf16 v[68:71], v[170:173], v[238:241], v[68:71]
	s_setprio 0
	s_barrier
	s_add_i32 s29, s29, s69
	v_lshl_add_u64 v[194:195], s[10:11], 0, v[150:151]
	s_mov_b32 m0, s29
	ds_read_b128 v[174:177], v185 offset:16384
	ds_read_b128 v[178:181], v185 offset:17408
	ds_read_b128 v[186:189], v185 offset:18432
	ds_read_b128 v[190:193], v185 offset:19456
	ds_read_b128 v[226:229], v185 offset:20480
	ds_read_b128 v[230:233], v185 offset:21504
	ds_read_b128 v[234:237], v185 offset:22528
	ds_read_b128 v[238:241], v185 offset:23552
	global_load_lds_dwordx4 v[194:195], off
	s_add_i32 m0, s29, 0x2000
	s_add_u32 s36, s10, 0x580000
	v_lshl_add_u64 v[198:199], s[10:11], 0, v[146:147]
	s_addc_u32 s37, s11, 0
	s_add_i32 s29, s38, s69
	global_load_lds_dwordx4 v[198:199], off
	v_lshl_add_u64 v[202:203], s[36:37], 0, v[150:151]
	s_mov_b32 m0, s29
	v_lshl_add_u64 v[204:205], s[12:13], 0, v[148:149]
	global_load_lds_dwordx4 v[202:203], off
	v_lshl_add_u64 v[202:203], s[36:37], 0, v[146:147]
	s_add_i32 m0, s29, 0x2000
	s_nop 0
	global_load_lds_dwordx4 v[202:203], off
	v_lshl_add_u64 v[202:203], s[12:13], 0, v[152:153]
	s_mov_b32 m0, s85
	s_nop 0
	global_load_lds_dwordx4 v[202:203], off
	s_mov_b32 m0, s86
	s_nop 0
	global_load_lds_dwordx4 v[204:205], off
	s_waitcnt vmcnt(8)
	s_waitcnt lgkmcnt(0)
	s_barrier
; #define PG8_STAGE(bufoff, gbase, voff) do { _Pragma("unroll") for (int _i = 0; _i < 2; ++_i) \
;         __builtin_amdgcn_global_load_lds((const unsigned*)((const char*)(gbase) + (voff)[_i]), (LAS unsigned*)(lds + (bufoff) + ldsw + _i * 8192), 16, 0, 0); } while (0)
; #define PG8_LDA(dst, b, h) do { _Pragma("unroll") for (int m = 0; m < 4; ++m) _Pragma("unroll") for (int k = 0; k < 2; ++k) dst[m][k] = *(const LAS bf16x8*)(lds + PG8_SA(b, h) + aoff + m * 2048 + k * 1024); } while (0)
; #define PG8_LDB(dst, b, h) do { _Pragma("unroll") for (int n = 0; n < 2; ++n) _Pragma("unroll") for (int k = 0; k < 2; ++k) dst[n][k] = *(const LAS bf16x8*)(lds + PG8_SB(b, h) + boff + n * 2048 + k * 1024); } while (0)
; #define PG8_MMA(ai, bj, At, Bt) do { __builtin_amdgcn_s_setprio(1); _Pragma("unroll") for (int m = 0; m < 4; ++m) _Pragma("unroll") for (int n = 0; n < 2; ++n) _Pragma("unroll") for (int k = 0; k < 2; ++k) \
;         acc[ai][bj][m][n] = __builtin_amdgcn_mfma_f32_16x16x32_bf16(Bt[n][k], At[m][k], acc[ai][bj][m][n], 0, 0, 0); __builtin_amdgcn_s_setprio(0); } while (0)
; #define PG8_WAIT_V(n) asm volatile("s_waitcnt vmcnt(" #n ")" ::: "memory")
; #define PG8_WAIT_L(n) asm volatile("s_waitcnt lgkmcnt(" #n ")" ::: "memory")
; #define PG8_BAR __builtin_amdgcn_s_barrier()
; #define PG8_SCHED __builtin_amdgcn_sched_barrier(0)
; template <class Epi>
; __device__ __forceinline__ void gemm_phase(ldsp lds, const Gemm g, const StaticOrder& S, const Epi& E, const int tid) {
;     ...
;             PG8_WAIT_V(8); PG8_WAIT_L(0); PG8_BAR; PG8_MMA(0, 0, At, B0); PG8_MMA(0, 1, At, B1); PG8_BAR; PG8_SCHED;
;             PG8_LDA(At, 0, 1); PG8_STAGE(PG8_SB(0, 0), b2, voffB); PG8_STAGE(PG8_SB(0, 1), b2 + hstepB, voffB); PG8_STAGE(PG8_SA(0, 0), a2, voffA);
;             PG8_WAIT_V(8); PG8_WAIT_L(0); PG8_BAR; PG8_MMA(1, 0, At, B0); PG8_MMA(1, 1, At, B1); PG8_BAR; PG8_SCHED;
;             PG8_LDB(B0, 1, 0); PG8_LDB(B1, 1, 1); PG8_SCHED; PG8_LDA(At, 1, 0); PG8_STAGE(PG8_SA(0, 1), a2 + hstepA, voffA);
;             PG8_WAIT_V(8); PG8_WAIT_L(0); PG8_BAR; PG8_MMA(0, 0, At, B0); PG8_MMA(0, 1, At, B1); PG8_BAR; PG8_SCHED;
;             PG8_LDA(At, 1, 1); PG8_STAGE(PG8_SB(1, 0), b3, voffB); PG8_STAGE(PG8_SB(1, 1), b3 + hstepB, voffB); PG8_STAGE(PG8_SA(1, 0), a3, voffA);
;             PG8_WAIT_V(8); PG8_WAIT_L(0); PG8_BAR; PG8_MMA(1, 0, At, B0); PG8_MMA(1, 1, At, B1); PG8_BAR; PG8_SCHED;
	s_setprio 1
	s_waitcnt lgkmcnt(0)
	v_mfma_f32_16x16x32_bf16 v[44:47], v[130:133], v[174:177], v[44:47]
	v_mfma_f32_16x16x32_bf16 v[0:3], v[138:141], v[174:177], v[0:3]
	v_mfma_f32_16x16x32_bf16 v[60:63], v[130:133], v[186:189], v[60:63]
	v_mfma_f32_16x16x32_bf16 v[28:31], v[138:141], v[186:189], v[28:31]
	v_mfma_f32_16x16x32_bf16 v[56:59], v[130:133], v[226:229], v[56:59]
	v_mfma_f32_16x16x32_bf16 v[24:27], v[138:141], v[226:229], v[24:27]
	v_mfma_f32_16x16x32_bf16 v[40:43], v[130:133], v[234:237], v[40:43]
	v_mfma_f32_16x16x32_bf16 v[4:7], v[138:141], v[234:237], v[4:7]
	v_mfma_f32_16x16x32_bf16 v[44:47], v[134:137], v[178:181], v[44:47]
	v_mfma_f32_16x16x32_bf16 v[0:3], v[142:145], v[178:181], v[0:3]
	v_mfma_f32_16x16x32_bf16 v[60:63], v[134:137], v[190:193], v[60:63]
	v_mfma_f32_16x16x32_bf16 v[28:31], v[142:145], v[190:193], v[28:31]
	v_mfma_f32_16x16x32_bf16 v[56:59], v[134:137], v[230:233], v[56:59]
	v_mfma_f32_16x16x32_bf16 v[24:27], v[142:145], v[230:233], v[24:27]
	v_mfma_f32_16x16x32_bf16 v[40:43], v[134:137], v[238:241], v[40:43]
	v_mfma_f32_16x16x32_bf16 v[4:7], v[142:145], v[238:241], v[4:7]
	s_setprio 0
	s_setprio 1
	v_mfma_f32_16x16x32_bf16 v[36:39], v[158:161], v[174:177], v[36:39]
	v_mfma_f32_16x16x32_bf16 v[8:11], v[166:169], v[174:177], v[8:11]
	v_mfma_f32_16x16x32_bf16 v[52:55], v[158:161], v[186:189], v[52:55]
	v_mfma_f32_16x16x32_bf16 v[20:23], v[166:169], v[186:189], v[20:23]
	v_mfma_f32_16x16x32_bf16 v[48:51], v[158:161], v[226:229], v[48:51]
	v_mfma_f32_16x16x32_bf16 v[16:19], v[166:169], v[226:229], v[16:19]
	v_mfma_f32_16x16x32_bf16 v[32:35], v[158:161], v[234:237], v[32:35]
	v_mfma_f32_16x16x32_bf16 v[12:15], v[166:169], v[234:237], v[12:15]
	v_mfma_f32_16x16x32_bf16 v[36:39], v[162:165], v[178:181], v[36:39]
	v_mfma_f32_16x16x32_bf16 v[8:11], v[170:173], v[178:181], v[8:11]
	v_mfma_f32_16x16x32_bf16 v[52:55], v[162:165], v[190:193], v[52:55]
	v_mfma_f32_16x16x32_bf16 v[20:23], v[170:173], v[190:193], v[20:23]
	v_mfma_f32_16x16x32_bf16 v[48:51], v[162:165], v[230:233], v[48:51]
	v_mfma_f32_16x16x32_bf16 v[16:19], v[170:173], v[230:233], v[16:19]
	v_mfma_f32_16x16x32_bf16 v[32:35], v[162:165], v[238:241], v[32:35]
	v_mfma_f32_16x16x32_bf16 v[12:15], v[170:173], v[238:241], v[12:15]
	s_setprio 0
	s_barrier
	s_add_i32 s29, 0, 0x18000
	v_add_u32_e32 v96, s29, v184
	s_add_i32 s36, 0, 0x1c000
	ds_read_b128 v[130:133], v96
	ds_read_b128 v[134:137], v96 offset:1024
	ds_read_b128 v[138:141], v96 offset:2048
	ds_read_b128 v[142:145], v96 offset:3072
	v_add_u32_e32 v96, s36, v184
	ds_read_b128 v[158:161], v96
	ds_read_b128 v[162:165], v96 offset:1024
	ds_read_b128 v[166:169], v96 offset:2048
	ds_read_b128 v[170:173], v96 offset:3072
	s_add_u32 s12, s12, 0x40000
	s_addc_u32 s13, s13, 0
	s_mov_b32 m0, s87
	v_lshl_add_u64 v[206:207], s[12:13], 0, v[152:153]
	ds_read_b128 v[174:177], v185 offset:32768
	ds_read_b128 v[178:181], v185 offset:33792
	ds_read_b128 v[186:189], v185 offset:34816
	ds_read_b128 v[190:193], v185 offset:35840
	ds_read_b128 v[226:229], v185 offset:36864
	ds_read_b128 v[230:233], v185 offset:37888
	ds_read_b128 v[234:237], v185 offset:38912
	ds_read_b128 v[238:241], v185 offset:39936
	global_load_lds_dwordx4 v[206:207], off
	v_lshl_add_u64 v[206:207], s[12:13], 0, v[148:149]
	s_mov_b32 m0, s48
	s_nop 0
	global_load_lds_dwordx4 v[206:207], off
	s_waitcnt vmcnt(8)
	s_waitcnt lgkmcnt(0)
	s_barrier
	s_setprio 1
	s_waitcnt lgkmcnt(0)
	v_mfma_f32_16x16x32_bf16 v[110:113], v[130:133], v[174:177], v[110:113]
	v_mfma_f32_16x16x32_bf16 v[76:79], v[138:141], v[174:177], v[76:79]
	v_mfma_f32_16x16x32_bf16 v[126:129], v[130:133], v[186:189], v[126:129]
	v_mfma_f32_16x16x32_bf16 v[92:95], v[138:141], v[186:189], v[92:95]
	v_mfma_f32_16x16x32_bf16 v[122:125], v[130:133], v[226:229], v[122:125]
	v_mfma_f32_16x16x32_bf16 v[88:91], v[138:141], v[226:229], v[88:91]
	v_mfma_f32_16x16x32_bf16 v[106:109], v[130:133], v[234:237], v[106:109]
	v_mfma_f32_16x16x32_bf16 v[72:75], v[138:141], v[234:237], v[72:75]
	v_mfma_f32_16x16x32_bf16 v[110:113], v[134:137], v[178:181], v[110:113]
	v_mfma_f32_16x16x32_bf16 v[76:79], v[142:145], v[178:181], v[76:79]
	v_mfma_f32_16x16x32_bf16 v[126:129], v[134:137], v[190:193], v[126:129]
	v_mfma_f32_16x16x32_bf16 v[92:95], v[142:145], v[190:193], v[92:95]
	v_mfma_f32_16x16x32_bf16 v[122:125], v[134:137], v[230:233], v[122:125]
	v_mfma_f32_16x16x32_bf16 v[88:91], v[142:145], v[230:233], v[88:91]
	v_mfma_f32_16x16x32_bf16 v[106:109], v[134:137], v[238:241], v[106:109]
	v_mfma_f32_16x16x32_bf16 v[72:75], v[142:145], v[238:241], v[72:75]
	s_setprio 0
	s_setprio 1
	v_mfma_f32_16x16x32_bf16 v[102:105], v[158:161], v[174:177], v[102:105]
	v_mfma_f32_16x16x32_bf16 v[64:67], v[166:169], v[174:177], v[64:67]
	v_mfma_f32_16x16x32_bf16 v[118:121], v[158:161], v[186:189], v[118:121]
	v_mfma_f32_16x16x32_bf16 v[84:87], v[166:169], v[186:189], v[84:87]
	v_mfma_f32_16x16x32_bf16 v[114:117], v[158:161], v[226:229], v[114:117]
	v_mfma_f32_16x16x32_bf16 v[80:83], v[166:169], v[226:229], v[80:83]
	v_mfma_f32_16x16x32_bf16 v[98:101], v[158:161], v[234:237], v[98:101]
	v_mfma_f32_16x16x32_bf16 v[68:71], v[166:169], v[234:237], v[68:71]
	v_mfma_f32_16x16x32_bf16 v[102:105], v[162:165], v[178:181], v[102:105]
	v_mfma_f32_16x16x32_bf16 v[64:67], v[170:173], v[178:181], v[64:67]
	v_mfma_f32_16x16x32_bf16 v[118:121], v[162:165], v[190:193], v[118:121]
	v_mfma_f32_16x16x32_bf16 v[84:87], v[170:173], v[190:193], v[84:87]
	v_mfma_f32_16x16x32_bf16 v[114:117], v[162:165], v[230:233], v[114:117]
	v_mfma_f32_16x16x32_bf16 v[80:83], v[170:173], v[230:233], v[80:83]
	v_mfma_f32_16x16x32_bf16 v[98:101], v[162:165], v[238:241], v[98:101]
	v_mfma_f32_16x16x32_bf16 v[68:71], v[170:173], v[238:241], v[68:71]
	s_setprio 0
	s_barrier
; #define PG8_STAGE(bufoff, gbase, voff) do { _Pragma("unroll") for (int _i = 0; _i < 2; ++_i) \
;         __builtin_amdgcn_global_load_lds((const unsigned*)((const char*)(gbase) + (voff)[_i]), (LAS unsigned*)(lds + (bufoff) + ldsw + _i * 8192), 16, 0, 0); } while (0)
; #define PG8_LDA(dst, b, h) do { _Pragma("unroll") for (int m = 0; m < 4; ++m) _Pragma("unroll") for (int k = 0; k < 2; ++k) dst[m][k] = *(const LAS bf16x8*)(lds + PG8_SA(b, h) + aoff + m * 2048 + k * 1024); } while (0)
; #define PG8_WAIT_V(n) asm volatile("s_waitcnt vmcnt(" #n ")" ::: "memory")
;     __device__ __forceinline__ void operator()(const f32x4 (&acc)[2][2][4][2], const Unit& u, int wr, int wc, int fr_in, int fq_in) const {
;         const int fr0_ = fr_in, fq0_ = fq_in;
;         char* base = (char*)(A2 + (size_t)(u.pm * BM) * DFF);
;         char* sbase = (char*)(side + (size_t)(u.pm * 16) * DFF2);
;         int fr_l = fr0_, fq_l = fq0_; asm volatile("" : "+v"(fr_l), "+v"(fq_l));
;         const int fr = fr_l, fq = fq_l;
;         const int ch0 = u.pn * HALF + wc * 32 + 8 * fq;
;         const unsigned off0 = (unsigned)(wr * 64 + fr) * (DFF * 2u) + (unsigned)ch0 * 2u;
;         const bool f0 = fr == 0, f15 = fr == 15;
;     ...
; #pragma unroll
;         for (int ai = 0; ai < 2; ++ai) {
;             f32x4 o[4]; u32x2 wlo[4];
; #pragma unroll
;             for (int n = 0; n < 2; ++n) {
;                 const int ch = ch0 + 4 * n;
; #pragma unroll
;                 for (int pass = 0; pass < 2; ++pass) {
;                     const int co = pass ? DFF : 0;
;                     const f32x4 k0 = *(const f32x4*)(fk + co + ch), k1 = *(const f32x4*)(fk + DFF2 + co + ch), k2 = *(const f32x4*)(fk + 2 * DFF2 + co + ch), bb = *(const f32x4*)(fb + co + ch);
; template <class Epi>
; __device__ __forceinline__ void gemm_phase(ldsp lds, const Gemm g, const StaticOrder& S, const Epi& E, const int tid) {
;     ...
;             PG8_WAIT_V(8); PG8_WAIT_L(0); PG8_BAR; PG8_MMA(0, 0, At, B0); PG8_MMA(0, 1, At, B1); PG8_BAR; PG8_SCHED;
;             PG8_LDA(At, 1, 1); PG8_STAGE(PG8_SB(1, 0), b3, voffB); PG8_STAGE(PG8_SB(1, 1), b3 + hstepB, voffB); PG8_STAGE(PG8_SA(1, 0), a3, voffA);
;             PG8_WAIT_V(8); PG8_WAIT_L(0); PG8_BAR; PG8_MMA(1, 0, At, B0); PG8_MMA(1, 1, At, B1); PG8_BAR; PG8_SCHED;
;         }
;         if (wr == 0) PG8_BAR;
;         if constexpr (!Epi::AFTER_DRAIN) E(acc, cur, wr, wc, fr, fq);
	s_add_i32 s12, s29, s69
	v_lshl_add_u64 v[194:195], v[194:195], 0, s[50:51]
	s_mov_b32 m0, s12
	ds_read_b128 v[174:177], v185 offset:49152
	ds_read_b128 v[178:181], v185 offset:50176
	ds_read_b128 v[186:189], v185 offset:51200
	ds_read_b128 v[190:193], v185 offset:52224
	ds_read_b128 v[226:229], v185 offset:53248
	ds_read_b128 v[230:233], v185 offset:54272
	ds_read_b128 v[234:237], v185 offset:55296
	ds_read_b128 v[238:241], v185 offset:56320
	global_load_lds_dwordx4 v[194:195], off
	s_add_i32 m0, s12, 0x2000
	s_add_u32 s10, s10, 0x580080
	v_lshl_add_u64 v[194:195], v[198:199], 0, s[50:51]
	s_addc_u32 s11, s11, 0
	s_add_i32 s12, s36, s69
	global_load_lds_dwordx4 v[194:195], off
	v_lshl_add_u64 v[194:195], s[10:11], 0, v[150:151]
	s_mov_b32 m0, s12
	s_nop 0
	global_load_lds_dwordx4 v[194:195], off
	v_lshl_add_u64 v[194:195], s[10:11], 0, v[146:147]
	s_add_i32 m0, s12, 0x2000
	s_nop 0
	global_load_lds_dwordx4 v[194:195], off
	v_lshl_add_u64 v[194:195], v[202:203], 0, s[50:51]
	s_mov_b32 m0, s15
	s_nop 0
	global_load_lds_dwordx4 v[194:195], off
	v_lshl_add_u64 v[194:195], v[204:205], 0, s[50:51]
	s_mov_b32 m0, s16
	s_nop 0
	global_load_lds_dwordx4 v[194:195], off
	s_waitcnt vmcnt(8)
	s_waitcnt lgkmcnt(0)
	s_barrier
	s_setprio 1
	s_waitcnt lgkmcnt(0)
	v_mfma_f32_16x16x32_bf16 v[44:47], v[130:133], v[174:177], v[44:47]
	v_mfma_f32_16x16x32_bf16 v[0:3], v[138:141], v[174:177], v[0:3]
	v_mfma_f32_16x16x32_bf16 v[60:63], v[130:133], v[186:189], v[60:63]
	v_mfma_f32_16x16x32_bf16 v[28:31], v[138:141], v[186:189], v[28:31]
	v_mfma_f32_16x16x32_bf16 v[56:59], v[130:133], v[226:229], v[56:59]
	v_mfma_f32_16x16x32_bf16 v[24:27], v[138:141], v[226:229], v[24:27]
	v_mfma_f32_16x16x32_bf16 v[40:43], v[130:133], v[234:237], v[40:43]
	v_mfma_f32_16x16x32_bf16 v[4:7], v[138:141], v[234:237], v[4:7]
	v_mfma_f32_16x16x32_bf16 v[44:47], v[134:137], v[178:181], v[44:47]
	v_mfma_f32_16x16x32_bf16 v[0:3], v[142:145], v[178:181], v[0:3]
	v_mfma_f32_16x16x32_bf16 v[60:63], v[134:137], v[190:193], v[60:63]
	v_mfma_f32_16x16x32_bf16 v[28:31], v[142:145], v[190:193], v[28:31]
	v_mfma_f32_16x16x32_bf16 v[56:59], v[134:137], v[230:233], v[56:59]
	v_mfma_f32_16x16x32_bf16 v[24:27], v[142:145], v[230:233], v[24:27]
	v_mfma_f32_16x16x32_bf16 v[40:43], v[134:137], v[238:241], v[40:43]
	v_mfma_f32_16x16x32_bf16 v[4:7], v[142:145], v[238:241], v[4:7]
	s_setprio 0
	s_setprio 1
	v_mfma_f32_16x16x32_bf16 v[36:39], v[158:161], v[174:177], v[36:39]
	v_mfma_f32_16x16x32_bf16 v[8:11], v[166:169], v[174:177], v[8:11]
	v_mfma_f32_16x16x32_bf16 v[52:55], v[158:161], v[186:189], v[52:55]
	v_mfma_f32_16x16x32_bf16 v[20:23], v[166:169], v[186:189], v[20:23]
	v_mfma_f32_16x16x32_bf16 v[48:51], v[158:161], v[226:229], v[48:51]
	v_mfma_f32_16x16x32_bf16 v[16:19], v[166:169], v[226:229], v[16:19]
	v_mfma_f32_16x16x32_bf16 v[32:35], v[158:161], v[234:237], v[32:35]
	v_mfma_f32_16x16x32_bf16 v[12:15], v[166:169], v[234:237], v[12:15]
	v_mfma_f32_16x16x32_bf16 v[36:39], v[162:165], v[178:181], v[36:39]
	v_mfma_f32_16x16x32_bf16 v[8:11], v[170:173], v[178:181], v[8:11]
	v_mfma_f32_16x16x32_bf16 v[52:55], v[162:165], v[190:193], v[52:55]
	v_mfma_f32_16x16x32_bf16 v[20:23], v[170:173], v[190:193], v[20:23]
	v_mfma_f32_16x16x32_bf16 v[48:51], v[162:165], v[230:233], v[48:51]
	v_mfma_f32_16x16x32_bf16 v[16:19], v[170:173], v[230:233], v[16:19]
	v_mfma_f32_16x16x32_bf16 v[32:35], v[162:165], v[238:241], v[32:35]
	v_mfma_f32_16x16x32_bf16 v[12:15], v[170:173], v[238:241], v[12:15]
	s_setprio 0
	s_barrier
	s_add_i32 s27, s27, 2
	s_add_u32 s6, s6, 0x100
	s_addc_u32 s7, s7, 0
	s_add_u32 s22, s22, 0x100
	s_addc_u32 s23, s23, 0
	s_cmp_gt_u32 s27, 13
	s_cbranch_scc0 .LBB0_1043
	v_lshrrev_b32_e32 v96, 6, v196
	s_nop 0
	v_readfirstlane_b32 s100, v96
	s_lshl_b32 s100, s100, 10
	s_add_i32 s100, s100, 0x20000
	v_lshl_add_u32 v213, v183, 4, s100
	s_cmp_eq_u32 s101, 0x7a9
	s_cbranch_scc1 .Lp7_staged
	v_and_b32_e32 v214, 63, v196
	v_bfe_u32 v130, v214, 2, 2
	v_bfe_u32 v131, v214, 4, 1
	v_lshrrev_b32_e32 v96, 5, v214
	v_and_b32_e32 v214, 3, v214
	s_lshl_b32 s0, s8, 7
	s_or_b32 s0, s0, s14
	v_lshl_add_u32 v214, v214, 3, s0
	v_lshl_add_u32 v214, v96, 2, v214
	v_lshlrev_b32_e32 v214, 2, v214
	v_mul_u32_u24_e32 v131, 0x2c00, v131
	v_add_u32_e32 v214, v214, v131
	v_cmp_eq_u32_e32 vcc, 3, v130
	v_mul_u32_u24_e32 v130, 0x5800, v130
	v_mov_b32_e32 v131, s53
	v_mov_b32_e32 v96, s54
	v_cndmask_b32_e64 v130, v130, 0, vcc
	v_add_u32_e32 v214, v214, v130
	v_mov_b32_e32 v130, s52
	v_cndmask_b32_e32 v130, v130, v96, vcc
	v_mov_b32_e32 v96, s55
	v_cndmask_b32_e32 v131, v131, v96, vcc
	v_add_co_u32_e32 v214, vcc, v130, v214
	s_nop 1
	v_addc_co_u32_e32 v215, vcc, 0, v131, vcc
	s_mov_b32 m0, s100
	s_nop 0
	global_load_lds_dwordx4 v[214:215], off
.Lp7_staged:
	s_and_b64 vcc, exec, s[58:59]
	s_cbranch_vccz .LBB0_1046
	s_barrier
.LBB0_1046:
	s_lshl_b32 s0, s42, 4
	s_mul_i32 s1, s42, 0x2c000
	s_mul_hi_i32 s0, s0, 0x2c00
	s_add_u32 s40, s46, s1
	s_addc_u32 s41, s64, s0
	s_load_dwordx2 s[0:1], s[62:63], 0xc0
	v_mul_u32_u24_e32 v194, 0x1600, v182
	v_lshl_add_u32 v194, v183, 4, v194
	v_cmp_gt_u32_e64 s[12:13], 2, v182
	v_cmp_lt_u32_e64 s[22:23], 13, v182
	v_add_u32_e32 v198, -12, v182
	s_or_b64 s[22:23], s[22:23], s[12:13]
	v_cndmask_b32_e64 v198, v198, v182, s[12:13]
	v_mul_u32_u24_e32 v195, 0x2c00, v198
	v_lshl_add_u32 v195, v183, 4, v195
	v_add_u32_e32 v197, 0x1600, v195
	s_sub_i32 s9, s100, 0x20000
	s_lshr_b32 s9, s9, 12
	s_lshl_b32 s10, s42, 8
	s_lshl_b32 s11, s9, 6
	s_add_i32 s10, s10, s11
	s_mul_i32 s10, s10, 0x1600
	s_lshl_b32 s11, s8, 7
	s_or_b32 s11, s11, s14
	s_lshl_b32 s11, s11, 1
	s_mul_i32 s9, s9, 0xb000
	s_waitcnt lgkmcnt(0)
	s_add_u32 s6, s0, 0x9400000
	s_addc_u32 s7, s1, 0
	s_add_u32 s6, s6, s10
	s_addc_u32 s7, s7, 0
	s_add_u32 s6, s6, s11
	s_addc_u32 s7, s7, 0
	s_add_u32 s10, s40, s9
	s_addc_u32 s11, s41, 0
	s_lshl_b32 s9, s8, 7
	s_or_b32 s9, s9, s14
	s_lshl_b32 s9, s9, 1
	s_add_u32 s10, s10, s9
	s_addc_u32 s11, s11, 0
	s_cmp_eq_u32 s101, 0x7a9
	s_cbranch_scc1 .Lp7_nowait
	s_waitcnt vmcnt(0)
; __device__ __forceinline__ unsigned cvt_pk_bf16(float lo, float hi) { unsigned r; asm volatile("v_cvt_pk_bf16_f32 %0, %1, %2" : "=v"(r) : "v"(lo), "v"(hi)); return r; }
;     __device__ __forceinline__ void operator()(const f32x4 (&acc)[2][2][4][2], const Unit& u, int wr, int wc, int fr_in, int fq_in) const {
;     ...
;                 const int ch = ch0 + 4 * n;
; #pragma unroll
;                 for (int pass = 0; pass < 2; ++pass) {
;                     const int co = pass ? DFF : 0;
;                     const f32x4 k0 = *(const f32x4*)(fk + co + ch), k1 = *(const f32x4*)(fk + DFF2 + co + ch), k2 = *(const f32x4*)(fk + 2 * DFF2 + co + ch), bb = *(const f32x4*)(fb + co + ch);
;                     f32x4 up_prev = (f32x4){0.f, 0.f, 0.f, 0.f}, up_cur, dn_cur, dn_next;
; #pragma unroll
;                     for (int j = 0; j < 4; ++j) dn_cur[j] = DPP_DN(acc[ai][pass][0][n][j]);
; #pragma unroll
;                     for (int m = 0; m < 4; ++m) {
;                         const f32x4 xv = acc[ai][pass][m][n];
; #pragma unroll
;                         for (int j = 0; j < 4; ++j) { up_cur[j] = DPP_UP(xv[j]); dn_next[j] = (m < 3) ? DPP_DN(acc[ai][pass][m < 3 ? m + 1 : 3][n][j]) : 0.f; }
;                         const f32x4 xp = f0 ? up_prev : up_cur, xn = f15 ? dn_next : dn_cur;
;                         const f32x4 c = (k0 * xp + k1 * xv) + (k2 * xn + bb);
;                         if (pass == 0) o[m] = c;
;                         else { f32x4 e;
; #pragma unroll
;                             for (int j = 0; j < 4; ++j) e[j] = __builtin_amdgcn_rcpf(1.0f + __builtin_amdgcn_exp2f(c[j] * -1.4426950408889634f));
;                             o[m] = o[m] * (c * e); }
;                         up_prev = up_cur; dn_cur = dn_next; }
;     ...
;                 if (fr < 2 || fr >= 14) { const int k = fr < 2 ? fr : fr - 12;
;                     const f32x4 xv = fr < 2 ? acc[ai][0][0][n] : acc[ai][0][3][n], yv = fr < 2 ? acc[ai][1][0][n] : acc[ai][1][3][n];
;                     char* sp = sbase + (size_t)((2 * ai + wr) * 4 + k) * (DFF2 * 2) + (size_t)ch * 2;
;                     u32x2 a, b; a.x = cvt_pk_bf16(xv[0], xv[1]); a.y = cvt_pk_bf16(xv[2], xv[3]); b.x = cvt_pk_bf16(yv[0], yv[1]); b.y = cvt_pk_bf16(yv[2], yv[3]);
;                     *(u32x2*)sp = a; *(u32x2*)(sp + DFF * 2) = b; }
.Lp7_nowait:
	ds_read_b128 v[130:133], v213 offset:0
	ds_read_b128 v[134:137], v213 offset:64
	ds_read_b128 v[138:141], v213 offset:128
	ds_read_b128 v[142:145], v213 offset:192
	ds_read_b128 v[158:161], v213 offset:256
	ds_read_b128 v[162:165], v213 offset:320
	ds_read_b128 v[166:169], v213 offset:384
	ds_read_b128 v[170:173], v213 offset:448
	v_cndmask_b32_e64 v202, v106, v110, s[12:13]
	v_cndmask_b32_e64 v203, v107, v111, s[12:13]
	v_cndmask_b32_e64 v204, v108, v112, s[12:13]
	v_cndmask_b32_e64 v205, v109, v113, s[12:13]
	v_cndmask_b32_e64 v206, v98, v102, s[12:13]
	v_cndmask_b32_e64 v207, v99, v103, s[12:13]
	v_cndmask_b32_e64 v208, v100, v104, s[12:13]
	v_cndmask_b32_e64 v209, v101, v105, s[12:13]
	v_cvt_pk_bf16_f32 v250, v202, v203
	v_cvt_pk_bf16_f32 v251, v204, v205
	v_cvt_pk_bf16_f32 v252, v206, v207
	v_cvt_pk_bf16_f32 v253, v208, v209
	s_mov_b64 s[42:43], exec
	s_and_b64 exec, exec, s[22:23]
	global_store_dwordx2 v195, v[250:251], s[10:11]
	global_store_dwordx2 v197, v[252:253], s[10:11]
	s_mov_b64 exec, s[42:43]
	s_waitcnt lgkmcnt(0)
	v_fma_f32 v174, v134, v110, v142
	v_fma_f32 v175, v135, v111, v143
	v_fma_f32 v176, v136, v112, v144
	v_fma_f32 v177, v137, v113, v145
	v_fma_f32 v178, v134, v126, v142
	v_fma_f32 v179, v135, v127, v143
	v_fma_f32 v180, v136, v128, v144
	v_fma_f32 v181, v137, v129, v145
	v_fma_f32 v186, v134, v122, v142
	v_fma_f32 v187, v135, v123, v143
	v_fma_f32 v188, v136, v124, v144
	v_fma_f32 v189, v137, v125, v145
	v_fma_f32 v190, v134, v106, v142
	v_fma_f32 v191, v135, v107, v143
	v_fma_f32 v192, v136, v108, v144
	v_fma_f32 v193, v137, v109, v145
	v_fmac_f32_dpp v174, v110, v130 row_shr:1 row_mask:0xf bank_mask:0xf
	v_fmac_f32_dpp v175, v111, v131 row_shr:1 row_mask:0xf bank_mask:0xf
	v_fmac_f32_dpp v176, v112, v132 row_shr:1 row_mask:0xf bank_mask:0xf
	v_fmac_f32_dpp v177, v113, v133 row_shr:1 row_mask:0xf bank_mask:0xf
	v_fmac_f32_dpp v174, v110, v138 row_shl:1 row_mask:0xf bank_mask:0xf
	v_fmac_f32_dpp v175, v111, v139 row_shl:1 row_mask:0xf bank_mask:0xf
	v_fmac_f32_dpp v176, v112, v140 row_shl:1 row_mask:0xf bank_mask:0xf
	v_fmac_f32_dpp v177, v113, v141 row_shl:1 row_mask:0xf bank_mask:0xf
	v_fmac_f32_dpp v174, v126, v138 row_shr:15 row_mask:0xf bank_mask:0xf
	v_fmac_f32_dpp v175, v127, v139 row_shr:15 row_mask:0xf bank_mask:0xf
	v_fmac_f32_dpp v176, v128, v140 row_shr:15 row_mask:0xf bank_mask:0xf
	v_fmac_f32_dpp v177, v129, v141 row_shr:15 row_mask:0xf bank_mask:0xf
	v_fmac_f32_dpp v178, v126, v130 row_shr:1 row_mask:0xf bank_mask:0xf
	v_fmac_f32_dpp v179, v127, v131 row_shr:1 row_mask:0xf bank_mask:0xf
	v_fmac_f32_dpp v180, v128, v132 row_shr:1 row_mask:0xf bank_mask:0xf
	v_fmac_f32_dpp v181, v129, v133 row_shr:1 row_mask:0xf bank_mask:0xf
	v_fmac_f32_dpp v178, v110, v130 row_shl:15 row_mask:0xf bank_mask:0xf
	v_fmac_f32_dpp v179, v111, v131 row_shl:15 row_mask:0xf bank_mask:0xf
	v_fmac_f32_dpp v180, v112, v132 row_shl:15 row_mask:0xf bank_mask:0xf
	v_fmac_f32_dpp v181, v113, v133 row_shl:15 row_mask:0xf bank_mask:0xf
	v_fmac_f32_dpp v178, v126, v138 row_shl:1 row_mask:0xf bank_mask:0xf
	v_fmac_f32_dpp v179, v127, v139 row_shl:1 row_mask:0xf bank_mask:0xf
	v_fmac_f32_dpp v180, v128, v140 row_shl:1 row_mask:0xf bank_mask:0xf
	v_fmac_f32_dpp v181, v129, v141 row_shl:1 row_mask:0xf bank_mask:0xf
	v_fmac_f32_dpp v178, v122, v138 row_shr:15 row_mask:0xf bank_mask:0xf
	v_fmac_f32_dpp v179, v123, v139 row_shr:15 row_mask:0xf bank_mask:0xf
	v_fmac_f32_dpp v180, v124, v140 row_shr:15 row_mask:0xf bank_mask:0xf
	v_fmac_f32_dpp v181, v125, v141 row_shr:15 row_mask:0xf bank_mask:0xf
	v_fmac_f32_dpp v186, v122, v130 row_shr:1 row_mask:0xf bank_mask:0xf
	v_fmac_f32_dpp v187, v123, v131 row_shr:1 row_mask:0xf bank_mask:0xf
	v_fmac_f32_dpp v188, v124, v132 row_shr:1 row_mask:0xf bank_mask:0xf
	v_fmac_f32_dpp v189, v125, v133 row_shr:1 row_mask:0xf bank_mask:0xf
	v_fmac_f32_dpp v186, v126, v130 row_shl:15 row_mask:0xf bank_mask:0xf
	v_fmac_f32_dpp v187, v127, v131 row_shl:15 row_mask:0xf bank_mask:0xf
	v_fmac_f32_dpp v188, v128, v132 row_shl:15 row_mask:0xf bank_mask:0xf
	v_fmac_f32_dpp v189, v129, v133 row_shl:15 row_mask:0xf bank_mask:0xf
	v_fmac_f32_dpp v186, v122, v138 row_shl:1 row_mask:0xf bank_mask:0xf
	v_fmac_f32_dpp v187, v123, v139 row_shl:1 row_mask:0xf bank_mask:0xf
	v_fmac_f32_dpp v188, v124, v140 row_shl:1 row_mask:0xf bank_mask:0xf
	v_fmac_f32_dpp v189, v125, v141 row_shl:1 row_mask:0xf bank_mask:0xf
	v_fmac_f32_dpp v186, v106, v138 row_shr:15 row_mask:0xf bank_mask:0xf
	v_fmac_f32_dpp v187, v107, v139 row_shr:15 row_mask:0xf bank_mask:0xf
	v_fmac_f32_dpp v188, v108, v140 row_shr:15 row_mask:0xf bank_mask:0xf
	v_fmac_f32_dpp v189, v109, v141 row_shr:15 row_mask:0xf bank_mask:0xf
	v_fmac_f32_dpp v190, v106, v130 row_shr:1 row_mask:0xf bank_mask:0xf
	v_fmac_f32_dpp v191, v107, v131 row_shr:1 row_mask:0xf bank_mask:0xf
	v_fmac_f32_dpp v192, v108, v132 row_shr:1 row_mask:0xf bank_mask:0xf
	v_fmac_f32_dpp v193, v109, v133 row_shr:1 row_mask:0xf bank_mask:0xf
	v_fmac_f32_dpp v190, v122, v130 row_shl:15 row_mask:0xf bank_mask:0xf
	v_fmac_f32_dpp v191, v123, v131 row_shl:15 row_mask:0xf bank_mask:0xf
	v_fmac_f32_dpp v192, v124, v132 row_shl:15 row_mask:0xf bank_mask:0xf
	v_fmac_f32_dpp v193, v125, v133 row_shl:15 row_mask:0xf bank_mask:0xf
	v_fmac_f32_dpp v190, v106, v138 row_shl:1 row_mask:0xf bank_mask:0xf
	v_fmac_f32_dpp v191, v107, v139 row_shl:1 row_mask:0xf bank_mask:0xf
	v_fmac_f32_dpp v192, v108, v140 row_shl:1 row_mask:0xf bank_mask:0xf
	v_fmac_f32_dpp v193, v109, v141 row_shl:1 row_mask:0xf bank_mask:0xf
	v_fma_f32 v226, v162, v102, v170
	v_fma_f32 v227, v163, v103, v171
	v_fma_f32 v228, v164, v104, v172
; #define DPP_UP(v) __int_as_float(__builtin_amdgcn_update_dpp(0, __float_as_int(v), 0x121, 0xf, 0xf, false))
; #define DPP_DN(v) __int_as_float(__builtin_amdgcn_update_dpp(0, __float_as_int(v), 0x12F, 0xf, 0xf, false))
;     __device__ __forceinline__ void operator()(const f32x4 (&acc)[2][2][4][2], const Unit& u, int wr, int wc, int fr_in, int fq_in) const {
;     ...
;                         for (int j = 0; j < 4; ++j) { up_cur[j] = DPP_UP(xv[j]); dn_next[j] = (m < 3) ? DPP_DN(acc[ai][pass][m < 3 ? m + 1 : 3][n][j]) : 0.f; }
;                         const f32x4 xp = f0 ? up_prev : up_cur, xn = f15 ? dn_next : dn_cur;
;                         const f32x4 c = (k0 * xp + k1 * xv) + (k2 * xn + bb);
;                         if (pass == 0) o[m] = c;
;                         else { f32x4 e;
; #pragma unroll
;                             for (int j = 0; j < 4; ++j) e[j] = __builtin_amdgcn_rcpf(1.0f + __builtin_amdgcn_exp2f(c[j] * -1.4426950408889634f));
;                             o[m] = o[m] * (c * e); }
	v_fma_f32 v229, v165, v105, v173
	v_fma_f32 v230, v162, v118, v170
	v_fma_f32 v231, v163, v119, v171
	v_fma_f32 v232, v164, v120, v172
	v_fma_f32 v233, v165, v121, v173
	v_fma_f32 v234, v162, v114, v170
	v_fma_f32 v235, v163, v115, v171
	v_fma_f32 v236, v164, v116, v172
	v_fma_f32 v237, v165, v117, v173
	v_fma_f32 v238, v162, v98, v170
	v_fma_f32 v239, v163, v99, v171
	v_fma_f32 v240, v164, v100, v172
	v_fma_f32 v241, v165, v101, v173
	v_fmac_f32_dpp v226, v102, v158 row_shr:1 row_mask:0xf bank_mask:0xf
	v_fmac_f32_dpp v227, v103, v159 row_shr:1 row_mask:0xf bank_mask:0xf
	v_fmac_f32_dpp v228, v104, v160 row_shr:1 row_mask:0xf bank_mask:0xf
	v_fmac_f32_dpp v229, v105, v161 row_shr:1 row_mask:0xf bank_mask:0xf
	v_fmac_f32_dpp v226, v102, v166 row_shl:1 row_mask:0xf bank_mask:0xf
	v_fmac_f32_dpp v227, v103, v167 row_shl:1 row_mask:0xf bank_mask:0xf
	v_fmac_f32_dpp v228, v104, v168 row_shl:1 row_mask:0xf bank_mask:0xf
	v_fmac_f32_dpp v229, v105, v169 row_shl:1 row_mask:0xf bank_mask:0xf
	v_fmac_f32_dpp v226, v118, v166 row_shr:15 row_mask:0xf bank_mask:0xf
	v_fmac_f32_dpp v227, v119, v167 row_shr:15 row_mask:0xf bank_mask:0xf
	v_fmac_f32_dpp v228, v120, v168 row_shr:15 row_mask:0xf bank_mask:0xf
	v_fmac_f32_dpp v229, v121, v169 row_shr:15 row_mask:0xf bank_mask:0xf
	v_fmac_f32_dpp v230, v118, v158 row_shr:1 row_mask:0xf bank_mask:0xf
	v_fmac_f32_dpp v231, v119, v159 row_shr:1 row_mask:0xf bank_mask:0xf
	v_fmac_f32_dpp v232, v120, v160 row_shr:1 row_mask:0xf bank_mask:0xf
	v_fmac_f32_dpp v233, v121, v161 row_shr:1 row_mask:0xf bank_mask:0xf
	v_fmac_f32_dpp v230, v102, v158 row_shl:15 row_mask:0xf bank_mask:0xf
	v_fmac_f32_dpp v231, v103, v159 row_shl:15 row_mask:0xf bank_mask:0xf
	v_fmac_f32_dpp v232, v104, v160 row_shl:15 row_mask:0xf bank_mask:0xf
	v_fmac_f32_dpp v233, v105, v161 row_shl:15 row_mask:0xf bank_mask:0xf
	v_fmac_f32_dpp v230, v118, v166 row_shl:1 row_mask:0xf bank_mask:0xf
	v_fmac_f32_dpp v231, v119, v167 row_shl:1 row_mask:0xf bank_mask:0xf
	v_fmac_f32_dpp v232, v120, v168 row_shl:1 row_mask:0xf bank_mask:0xf
	v_fmac_f32_dpp v233, v121, v169 row_shl:1 row_mask:0xf bank_mask:0xf
	v_fmac_f32_dpp v230, v114, v166 row_shr:15 row_mask:0xf bank_mask:0xf
	v_fmac_f32_dpp v231, v115, v167 row_shr:15 row_mask:0xf bank_mask:0xf
	v_fmac_f32_dpp v232, v116, v168 row_shr:15 row_mask:0xf bank_mask:0xf
	v_fmac_f32_dpp v233, v117, v169 row_shr:15 row_mask:0xf bank_mask:0xf
	v_fmac_f32_dpp v234, v114, v158 row_shr:1 row_mask:0xf bank_mask:0xf
	v_fmac_f32_dpp v235, v115, v159 row_shr:1 row_mask:0xf bank_mask:0xf
	v_fmac_f32_dpp v236, v116, v160 row_shr:1 row_mask:0xf bank_mask:0xf
	v_fmac_f32_dpp v237, v117, v161 row_shr:1 row_mask:0xf bank_mask:0xf
	v_fmac_f32_dpp v234, v118, v158 row_shl:15 row_mask:0xf bank_mask:0xf
	v_fmac_f32_dpp v235, v119, v159 row_shl:15 row_mask:0xf bank_mask:0xf
	v_fmac_f32_dpp v236, v120, v160 row_shl:15 row_mask:0xf bank_mask:0xf
	v_fmac_f32_dpp v237, v121, v161 row_shl:15 row_mask:0xf bank_mask:0xf
	v_fmac_f32_dpp v234, v114, v166 row_shl:1 row_mask:0xf bank_mask:0xf
	v_fmac_f32_dpp v235, v115, v167 row_shl:1 row_mask:0xf bank_mask:0xf
	v_fmac_f32_dpp v236, v116, v168 row_shl:1 row_mask:0xf bank_mask:0xf
	v_fmac_f32_dpp v237, v117, v169 row_shl:1 row_mask:0xf bank_mask:0xf
	v_fmac_f32_dpp v234, v98, v166 row_shr:15 row_mask:0xf bank_mask:0xf
	v_fmac_f32_dpp v235, v99, v167 row_shr:15 row_mask:0xf bank_mask:0xf
	v_fmac_f32_dpp v236, v100, v168 row_shr:15 row_mask:0xf bank_mask:0xf
	v_fmac_f32_dpp v237, v101, v169 row_shr:15 row_mask:0xf bank_mask:0xf
	v_fmac_f32_dpp v238, v98, v158 row_shr:1 row_mask:0xf bank_mask:0xf
	v_fmac_f32_dpp v239, v99, v159 row_shr:1 row_mask:0xf bank_mask:0xf
	v_fmac_f32_dpp v240, v100, v160 row_shr:1 row_mask:0xf bank_mask:0xf
	v_fmac_f32_dpp v241, v101, v161 row_shr:1 row_mask:0xf bank_mask:0xf
	v_fmac_f32_dpp v238, v114, v158 row_shl:15 row_mask:0xf bank_mask:0xf
	v_fmac_f32_dpp v239, v115, v159 row_shl:15 row_mask:0xf bank_mask:0xf
	v_fmac_f32_dpp v240, v116, v160 row_shl:15 row_mask:0xf bank_mask:0xf
	v_fmac_f32_dpp v241, v117, v161 row_shl:15 row_mask:0xf bank_mask:0xf
	v_fmac_f32_dpp v238, v98, v166 row_shl:1 row_mask:0xf bank_mask:0xf
	v_fmac_f32_dpp v239, v99, v167 row_shl:1 row_mask:0xf bank_mask:0xf
	v_fmac_f32_dpp v240, v100, v168 row_shl:1 row_mask:0xf bank_mask:0xf
	v_fmac_f32_dpp v241, v101, v169 row_shl:1 row_mask:0xf bank_mask:0xf
	v_mul_f32_e32 v242, 0xbfb8aa3b, v226
	v_mul_f32_e32 v243, 0xbfb8aa3b, v227
	v_mul_f32_e32 v244, 0xbfb8aa3b, v228
	v_mul_f32_e32 v245, 0xbfb8aa3b, v229
	v_mul_f32_e32 v246, 0xbfb8aa3b, v230
	v_mul_f32_e32 v247, 0xbfb8aa3b, v231
	v_mul_f32_e32 v248, 0xbfb8aa3b, v232
	v_mul_f32_e32 v249, 0xbfb8aa3b, v233
	v_exp_f32_e32 v242, v242
	v_exp_f32_e32 v243, v243
	v_exp_f32_e32 v244, v244
	v_exp_f32_e32 v245, v245
	v_exp_f32_e32 v246, v246
	v_exp_f32_e32 v247, v247
	v_exp_f32_e32 v248, v248
	v_exp_f32_e32 v249, v249
	v_add_f32_e32 v242, 1.0, v242
	v_add_f32_e32 v243, 1.0, v243
	v_add_f32_e32 v244, 1.0, v244
	v_add_f32_e32 v245, 1.0, v245
	v_add_f32_e32 v246, 1.0, v246
	v_add_f32_e32 v247, 1.0, v247
	v_add_f32_e32 v248, 1.0, v248
	v_add_f32_e32 v249, 1.0, v249
	v_rcp_f32_e32 v242, v242
	v_rcp_f32_e32 v243, v243
	v_rcp_f32_e32 v244, v244
	v_rcp_f32_e32 v245, v245
	v_rcp_f32_e32 v246, v246
	v_rcp_f32_e32 v247, v247
	v_rcp_f32_e32 v248, v248
	v_rcp_f32_e32 v249, v249
	v_mul_f32_e32 v242, v226, v242
	v_mul_f32_e32 v243, v227, v243
	v_mul_f32_e32 v244, v228, v244
	v_mul_f32_e32 v245, v229, v245
	v_mul_f32_e32 v246, v230, v246
	v_mul_f32_e32 v247, v231, v247
	v_mul_f32_e32 v248, v232, v248
	v_mul_f32_e32 v249, v233, v249
	v_mul_f32_e32 v174, v174, v242
;     __device__ __forceinline__ void operator()(const f32x4 (&acc)[2][2][4][2], const Unit& u, int wr, int wc, int fr_in, int fq_in) const {
;     ...
;                 const int ch = ch0 + 4 * n;
; #pragma unroll
;                 for (int pass = 0; pass < 2; ++pass) {
;                     const int co = pass ? DFF : 0;
;                     const f32x4 k0 = *(const f32x4*)(fk + co + ch), k1 = *(const f32x4*)(fk + DFF2 + co + ch), k2 = *(const f32x4*)(fk + 2 * DFF2 + co + ch), bb = *(const f32x4*)(fb + co + ch);
;                     f32x4 up_prev = (f32x4){0.f, 0.f, 0.f, 0.f}, up_cur, dn_cur, dn_next;
; #pragma unroll
;                     for (int j = 0; j < 4; ++j) dn_cur[j] = DPP_DN(acc[ai][pass][0][n][j]);
; #pragma unroll
;                     for (int m = 0; m < 4; ++m) {
;                         const f32x4 xv = acc[ai][pass][m][n];
; #pragma unroll
;                         for (int j = 0; j < 4; ++j) { up_cur[j] = DPP_UP(xv[j]); dn_next[j] = (m < 3) ? DPP_DN(acc[ai][pass][m < 3 ? m + 1 : 3][n][j]) : 0.f; }
;     ...
;                             for (int j = 0; j < 4; ++j) e[j] = __builtin_amdgcn_rcpf(1.0f + __builtin_amdgcn_exp2f(c[j] * -1.4426950408889634f));
;                             o[m] = o[m] * (c * e); }
;                         up_prev = up_cur; dn_cur = dn_next; }
;                 }
;                 if (n == 0) {
; #pragma unroll
;                     for (int m = 0; m < 4; ++m) { wlo[m].x = cvt_pk_bf16(o[m][0], o[m][1]); wlo[m].y = cvt_pk_bf16(o[m][2], o[m][3]); }
;                 } else {
; #pragma unroll
;                     for (int m = 0; m < 4; ++m) { u32x4 w; w.x = wlo[m].x; w.y = wlo[m].y; w.z = cvt_pk_bf16(o[m][0], o[m][1]); w.w = cvt_pk_bf16(o[m][2], o[m][3]);
;                         *(u32x4*)(base + off0 + (unsigned)(ai * HALF + m * 16) * (DFF * 2u)) = w; }
;                 }
;                 if (fr < 2 || fr >= 14) { const int k = fr < 2 ? fr : fr - 12;
;                     const f32x4 xv = fr < 2 ? acc[ai][0][0][n] : acc[ai][0][3][n], yv = fr < 2 ? acc[ai][1][0][n] : acc[ai][1][3][n];
;                     char* sp = sbase + (size_t)((2 * ai + wr) * 4 + k) * (DFF2 * 2) + (size_t)ch * 2;
;                     u32x2 a, b; a.x = cvt_pk_bf16(xv[0], xv[1]); a.y = cvt_pk_bf16(xv[2], xv[3]); b.x = cvt_pk_bf16(yv[0], yv[1]); b.y = cvt_pk_bf16(yv[2], yv[3]);
;                     *(u32x2*)sp = a; *(u32x2*)(sp + DFF * 2) = b; }
	v_mul_f32_e32 v175, v175, v243
	v_mul_f32_e32 v176, v176, v244
	v_mul_f32_e32 v177, v177, v245
	v_mul_f32_e32 v178, v178, v246
	v_mul_f32_e32 v179, v179, v247
	v_mul_f32_e32 v180, v180, v248
	v_mul_f32_e32 v181, v181, v249
	v_mul_f32_e32 v242, 0xbfb8aa3b, v234
	v_mul_f32_e32 v243, 0xbfb8aa3b, v235
	v_mul_f32_e32 v244, 0xbfb8aa3b, v236
	v_mul_f32_e32 v245, 0xbfb8aa3b, v237
	v_mul_f32_e32 v246, 0xbfb8aa3b, v238
	v_mul_f32_e32 v247, 0xbfb8aa3b, v239
	v_mul_f32_e32 v248, 0xbfb8aa3b, v240
	v_mul_f32_e32 v249, 0xbfb8aa3b, v241
	v_exp_f32_e32 v242, v242
	v_exp_f32_e32 v243, v243
	v_exp_f32_e32 v244, v244
	v_exp_f32_e32 v245, v245
	v_exp_f32_e32 v246, v246
	v_exp_f32_e32 v247, v247
	v_exp_f32_e32 v248, v248
	v_exp_f32_e32 v249, v249
	v_add_f32_e32 v242, 1.0, v242
	v_add_f32_e32 v243, 1.0, v243
	v_add_f32_e32 v244, 1.0, v244
	v_add_f32_e32 v245, 1.0, v245
	v_add_f32_e32 v246, 1.0, v246
	v_add_f32_e32 v247, 1.0, v247
	v_add_f32_e32 v248, 1.0, v248
	v_add_f32_e32 v249, 1.0, v249
	v_rcp_f32_e32 v242, v242
	v_rcp_f32_e32 v243, v243
	v_rcp_f32_e32 v244, v244
	v_rcp_f32_e32 v245, v245
	v_rcp_f32_e32 v246, v246
	v_rcp_f32_e32 v247, v247
	v_rcp_f32_e32 v248, v248
	v_rcp_f32_e32 v249, v249
	v_mul_f32_e32 v242, v234, v242
	v_mul_f32_e32 v243, v235, v243
	v_mul_f32_e32 v244, v236, v244
	v_mul_f32_e32 v245, v237, v245
	v_mul_f32_e32 v246, v238, v246
	v_mul_f32_e32 v247, v239, v247
	v_mul_f32_e32 v248, v240, v248
	v_mul_f32_e32 v249, v241, v249
	v_mul_f32_e32 v186, v186, v242
	v_mul_f32_e32 v187, v187, v243
	v_mul_f32_e32 v188, v188, v244
	v_mul_f32_e32 v189, v189, v245
	v_mul_f32_e32 v190, v190, v246
	v_mul_f32_e32 v191, v191, v247
	v_mul_f32_e32 v192, v192, v248
	v_mul_f32_e32 v193, v193, v249
	v_cvt_pk_bf16_f32 v110, v174, v175
	v_cvt_pk_bf16_f32 v111, v176, v177
	v_cvt_pk_bf16_f32 v126, v178, v179
	v_cvt_pk_bf16_f32 v127, v180, v181
	v_cvt_pk_bf16_f32 v122, v186, v187
	v_cvt_pk_bf16_f32 v123, v188, v189
	v_cvt_pk_bf16_f32 v106, v190, v191
	v_cvt_pk_bf16_f32 v107, v192, v193
	v_cndmask_b32_e64 v202, v40, v44, s[12:13]
	v_cndmask_b32_e64 v203, v41, v45, s[12:13]
	v_cndmask_b32_e64 v204, v42, v46, s[12:13]
	v_cndmask_b32_e64 v205, v43, v47, s[12:13]
	v_cndmask_b32_e64 v206, v32, v36, s[12:13]
	v_cndmask_b32_e64 v207, v33, v37, s[12:13]
	v_cndmask_b32_e64 v208, v34, v38, s[12:13]
	v_cndmask_b32_e64 v209, v35, v39, s[12:13]
	v_cvt_pk_bf16_f32 v250, v202, v203
	v_cvt_pk_bf16_f32 v251, v204, v205
	v_cvt_pk_bf16_f32 v252, v206, v207
	v_cvt_pk_bf16_f32 v253, v208, v209
	s_add_u32 s10, s10, 0x16000
	s_addc_u32 s11, s11, 0
	s_mov_b64 s[42:43], exec
	s_and_b64 exec, exec, s[22:23]
	global_store_dwordx2 v195, v[250:251], s[10:11]
	global_store_dwordx2 v197, v[252:253], s[10:11]
	s_mov_b64 exec, s[42:43]
	v_fma_f32 v174, v134, v44, v142
	v_fma_f32 v175, v135, v45, v143
	v_fma_f32 v176, v136, v46, v144
	v_fma_f32 v177, v137, v47, v145
	v_fma_f32 v178, v134, v60, v142
	v_fma_f32 v179, v135, v61, v143
	v_fma_f32 v180, v136, v62, v144
	v_fma_f32 v181, v137, v63, v145
	v_fma_f32 v186, v134, v56, v142
	v_fma_f32 v187, v135, v57, v143
	v_fma_f32 v188, v136, v58, v144
	v_fma_f32 v189, v137, v59, v145
	v_fma_f32 v190, v134, v40, v142
	v_fma_f32 v191, v135, v41, v143
	v_fma_f32 v192, v136, v42, v144
	v_fma_f32 v193, v137, v43, v145
	v_fmac_f32_dpp v174, v44, v130 row_shr:1 row_mask:0xf bank_mask:0xf
	v_fmac_f32_dpp v175, v45, v131 row_shr:1 row_mask:0xf bank_mask:0xf
	v_fmac_f32_dpp v176, v46, v132 row_shr:1 row_mask:0xf bank_mask:0xf
	v_fmac_f32_dpp v177, v47, v133 row_shr:1 row_mask:0xf bank_mask:0xf
	v_fmac_f32_dpp v174, v44, v138 row_shl:1 row_mask:0xf bank_mask:0xf
	v_fmac_f32_dpp v175, v45, v139 row_shl:1 row_mask:0xf bank_mask:0xf
	v_fmac_f32_dpp v176, v46, v140 row_shl:1 row_mask:0xf bank_mask:0xf
	v_fmac_f32_dpp v177, v47, v141 row_shl:1 row_mask:0xf bank_mask:0xf
	v_fmac_f32_dpp v174, v60, v138 row_shr:15 row_mask:0xf bank_mask:0xf
	v_fmac_f32_dpp v175, v61, v139 row_shr:15 row_mask:0xf bank_mask:0xf
	v_fmac_f32_dpp v176, v62, v140 row_shr:15 row_mask:0xf bank_mask:0xf
	v_fmac_f32_dpp v177, v63, v141 row_shr:15 row_mask:0xf bank_mask:0xf
	v_fmac_f32_dpp v178, v60, v130 row_shr:1 row_mask:0xf bank_mask:0xf
	v_fmac_f32_dpp v179, v61, v131 row_shr:1 row_mask:0xf bank_mask:0xf
	v_fmac_f32_dpp v180, v62, v132 row_shr:1 row_mask:0xf bank_mask:0xf
	v_fmac_f32_dpp v181, v63, v133 row_shr:1 row_mask:0xf bank_mask:0xf
	v_fmac_f32_dpp v178, v44, v130 row_shl:15 row_mask:0xf bank_mask:0xf
	v_fmac_f32_dpp v179, v45, v131 row_shl:15 row_mask:0xf bank_mask:0xf
	v_fmac_f32_dpp v180, v46, v132 row_shl:15 row_mask:0xf bank_mask:0xf
	v_fmac_f32_dpp v181, v47, v133 row_shl:15 row_mask:0xf bank_mask:0xf
	v_fmac_f32_dpp v178, v60, v138 row_shl:1 row_mask:0xf bank_mask:0xf
	v_fmac_f32_dpp v179, v61, v139 row_shl:1 row_mask:0xf bank_mask:0xf
	v_fmac_f32_dpp v180, v62, v140 row_shl:1 row_mask:0xf bank_mask:0xf
	v_fmac_f32_dpp v181, v63, v141 row_shl:1 row_mask:0xf bank_mask:0xf
	v_fmac_f32_dpp v178, v56, v138 row_shr:15 row_mask:0xf bank_mask:0xf
	v_fmac_f32_dpp v179, v57, v139 row_shr:15 row_mask:0xf bank_mask:0xf
	v_fmac_f32_dpp v180, v58, v140 row_shr:15 row_mask:0xf bank_mask:0xf
	v_fmac_f32_dpp v181, v59, v141 row_shr:15 row_mask:0xf bank_mask:0xf
	v_fmac_f32_dpp v186, v56, v130 row_shr:1 row_mask:0xf bank_mask:0xf
	v_fmac_f32_dpp v187, v57, v131 row_shr:1 row_mask:0xf bank_mask:0xf
	v_fmac_f32_dpp v188, v58, v132 row_shr:1 row_mask:0xf bank_mask:0xf
	v_fmac_f32_dpp v189, v59, v133 row_shr:1 row_mask:0xf bank_mask:0xf
	v_fmac_f32_dpp v186, v60, v130 row_shl:15 row_mask:0xf bank_mask:0xf
	v_fmac_f32_dpp v187, v61, v131 row_shl:15 row_mask:0xf bank_mask:0xf
; #define DPP_UP(v) __int_as_float(__builtin_amdgcn_update_dpp(0, __float_as_int(v), 0x121, 0xf, 0xf, false))
; #define DPP_DN(v) __int_as_float(__builtin_amdgcn_update_dpp(0, __float_as_int(v), 0x12F, 0xf, 0xf, false))
;     __device__ __forceinline__ void operator()(const f32x4 (&acc)[2][2][4][2], const Unit& u, int wr, int wc, int fr_in, int fq_in) const {
;     ...
;                     const f32x4 k0 = *(const f32x4*)(fk + co + ch), k1 = *(const f32x4*)(fk + DFF2 + co + ch), k2 = *(const f32x4*)(fk + 2 * DFF2 + co + ch), bb = *(const f32x4*)(fb + co + ch);
;                     f32x4 up_prev = (f32x4){0.f, 0.f, 0.f, 0.f}, up_cur, dn_cur, dn_next;
; #pragma unroll
;                     for (int j = 0; j < 4; ++j) dn_cur[j] = DPP_DN(acc[ai][pass][0][n][j]);
; #pragma unroll
;                     for (int m = 0; m < 4; ++m) {
;                         const f32x4 xv = acc[ai][pass][m][n];
; #pragma unroll
;                         for (int j = 0; j < 4; ++j) { up_cur[j] = DPP_UP(xv[j]); dn_next[j] = (m < 3) ? DPP_DN(acc[ai][pass][m < 3 ? m + 1 : 3][n][j]) : 0.f; }
;                         const f32x4 xp = f0 ? up_prev : up_cur, xn = f15 ? dn_next : dn_cur;
;                         const f32x4 c = (k0 * xp + k1 * xv) + (k2 * xn + bb);
	v_fmac_f32_dpp v188, v62, v132 row_shl:15 row_mask:0xf bank_mask:0xf
	v_fmac_f32_dpp v189, v63, v133 row_shl:15 row_mask:0xf bank_mask:0xf
	v_fmac_f32_dpp v186, v56, v138 row_shl:1 row_mask:0xf bank_mask:0xf
	v_fmac_f32_dpp v187, v57, v139 row_shl:1 row_mask:0xf bank_mask:0xf
	v_fmac_f32_dpp v188, v58, v140 row_shl:1 row_mask:0xf bank_mask:0xf
	v_fmac_f32_dpp v189, v59, v141 row_shl:1 row_mask:0xf bank_mask:0xf
	v_fmac_f32_dpp v186, v40, v138 row_shr:15 row_mask:0xf bank_mask:0xf
	v_fmac_f32_dpp v187, v41, v139 row_shr:15 row_mask:0xf bank_mask:0xf
	v_fmac_f32_dpp v188, v42, v140 row_shr:15 row_mask:0xf bank_mask:0xf
	v_fmac_f32_dpp v189, v43, v141 row_shr:15 row_mask:0xf bank_mask:0xf
	v_fmac_f32_dpp v190, v40, v130 row_shr:1 row_mask:0xf bank_mask:0xf
	v_fmac_f32_dpp v191, v41, v131 row_shr:1 row_mask:0xf bank_mask:0xf
	v_fmac_f32_dpp v192, v42, v132 row_shr:1 row_mask:0xf bank_mask:0xf
	v_fmac_f32_dpp v193, v43, v133 row_shr:1 row_mask:0xf bank_mask:0xf
	v_fmac_f32_dpp v190, v56, v130 row_shl:15 row_mask:0xf bank_mask:0xf
	v_fmac_f32_dpp v191, v57, v131 row_shl:15 row_mask:0xf bank_mask:0xf
	v_fmac_f32_dpp v192, v58, v132 row_shl:15 row_mask:0xf bank_mask:0xf
	v_fmac_f32_dpp v193, v59, v133 row_shl:15 row_mask:0xf bank_mask:0xf
	v_fmac_f32_dpp v190, v40, v138 row_shl:1 row_mask:0xf bank_mask:0xf
	v_fmac_f32_dpp v191, v41, v139 row_shl:1 row_mask:0xf bank_mask:0xf
	v_fmac_f32_dpp v192, v42, v140 row_shl:1 row_mask:0xf bank_mask:0xf
	v_fmac_f32_dpp v193, v43, v141 row_shl:1 row_mask:0xf bank_mask:0xf
	v_fma_f32 v226, v162, v36, v170
	v_fma_f32 v227, v163, v37, v171
	v_fma_f32 v228, v164, v38, v172
	v_fma_f32 v229, v165, v39, v173
	v_fma_f32 v230, v162, v52, v170
	v_fma_f32 v231, v163, v53, v171
	v_fma_f32 v232, v164, v54, v172
	v_fma_f32 v233, v165, v55, v173
	v_fma_f32 v234, v162, v48, v170
	v_fma_f32 v235, v163, v49, v171
	v_fma_f32 v236, v164, v50, v172
	v_fma_f32 v237, v165, v51, v173
	v_fma_f32 v238, v162, v32, v170
	v_fma_f32 v239, v163, v33, v171
	v_fma_f32 v240, v164, v34, v172
	v_fma_f32 v241, v165, v35, v173
	v_fmac_f32_dpp v226, v36, v158 row_shr:1 row_mask:0xf bank_mask:0xf
	v_fmac_f32_dpp v227, v37, v159 row_shr:1 row_mask:0xf bank_mask:0xf
	v_fmac_f32_dpp v228, v38, v160 row_shr:1 row_mask:0xf bank_mask:0xf
	v_fmac_f32_dpp v229, v39, v161 row_shr:1 row_mask:0xf bank_mask:0xf
	v_fmac_f32_dpp v226, v36, v166 row_shl:1 row_mask:0xf bank_mask:0xf
	v_fmac_f32_dpp v227, v37, v167 row_shl:1 row_mask:0xf bank_mask:0xf
	v_fmac_f32_dpp v228, v38, v168 row_shl:1 row_mask:0xf bank_mask:0xf
	v_fmac_f32_dpp v229, v39, v169 row_shl:1 row_mask:0xf bank_mask:0xf
	v_fmac_f32_dpp v226, v52, v166 row_shr:15 row_mask:0xf bank_mask:0xf
	v_fmac_f32_dpp v227, v53, v167 row_shr:15 row_mask:0xf bank_mask:0xf
	v_fmac_f32_dpp v228, v54, v168 row_shr:15 row_mask:0xf bank_mask:0xf
	v_fmac_f32_dpp v229, v55, v169 row_shr:15 row_mask:0xf bank_mask:0xf
	v_fmac_f32_dpp v230, v52, v158 row_shr:1 row_mask:0xf bank_mask:0xf
	v_fmac_f32_dpp v231, v53, v159 row_shr:1 row_mask:0xf bank_mask:0xf
	v_fmac_f32_dpp v232, v54, v160 row_shr:1 row_mask:0xf bank_mask:0xf
	v_fmac_f32_dpp v233, v55, v161 row_shr:1 row_mask:0xf bank_mask:0xf
	v_fmac_f32_dpp v230, v36, v158 row_shl:15 row_mask:0xf bank_mask:0xf
	v_fmac_f32_dpp v231, v37, v159 row_shl:15 row_mask:0xf bank_mask:0xf
	v_fmac_f32_dpp v232, v38, v160 row_shl:15 row_mask:0xf bank_mask:0xf
	v_fmac_f32_dpp v233, v39, v161 row_shl:15 row_mask:0xf bank_mask:0xf
	v_fmac_f32_dpp v230, v52, v166 row_shl:1 row_mask:0xf bank_mask:0xf
	v_fmac_f32_dpp v231, v53, v167 row_shl:1 row_mask:0xf bank_mask:0xf
	v_fmac_f32_dpp v232, v54, v168 row_shl:1 row_mask:0xf bank_mask:0xf
	v_fmac_f32_dpp v233, v55, v169 row_shl:1 row_mask:0xf bank_mask:0xf
	v_fmac_f32_dpp v230, v48, v166 row_shr:15 row_mask:0xf bank_mask:0xf
	v_fmac_f32_dpp v231, v49, v167 row_shr:15 row_mask:0xf bank_mask:0xf
	v_fmac_f32_dpp v232, v50, v168 row_shr:15 row_mask:0xf bank_mask:0xf
	v_fmac_f32_dpp v233, v51, v169 row_shr:15 row_mask:0xf bank_mask:0xf
	v_fmac_f32_dpp v234, v48, v158 row_shr:1 row_mask:0xf bank_mask:0xf
	v_fmac_f32_dpp v235, v49, v159 row_shr:1 row_mask:0xf bank_mask:0xf
	v_fmac_f32_dpp v236, v50, v160 row_shr:1 row_mask:0xf bank_mask:0xf
	v_fmac_f32_dpp v237, v51, v161 row_shr:1 row_mask:0xf bank_mask:0xf
	v_fmac_f32_dpp v234, v52, v158 row_shl:15 row_mask:0xf bank_mask:0xf
	v_fmac_f32_dpp v235, v53, v159 row_shl:15 row_mask:0xf bank_mask:0xf
	v_fmac_f32_dpp v236, v54, v160 row_shl:15 row_mask:0xf bank_mask:0xf
	v_fmac_f32_dpp v237, v55, v161 row_shl:15 row_mask:0xf bank_mask:0xf
	v_fmac_f32_dpp v234, v48, v166 row_shl:1 row_mask:0xf bank_mask:0xf
	v_fmac_f32_dpp v235, v49, v167 row_shl:1 row_mask:0xf bank_mask:0xf
	v_fmac_f32_dpp v236, v50, v168 row_shl:1 row_mask:0xf bank_mask:0xf
	v_fmac_f32_dpp v237, v51, v169 row_shl:1 row_mask:0xf bank_mask:0xf
	v_fmac_f32_dpp v234, v32, v166 row_shr:15 row_mask:0xf bank_mask:0xf
	v_fmac_f32_dpp v235, v33, v167 row_shr:15 row_mask:0xf bank_mask:0xf
	v_fmac_f32_dpp v236, v34, v168 row_shr:15 row_mask:0xf bank_mask:0xf
	v_fmac_f32_dpp v237, v35, v169 row_shr:15 row_mask:0xf bank_mask:0xf
	v_fmac_f32_dpp v238, v32, v158 row_shr:1 row_mask:0xf bank_mask:0xf
	v_fmac_f32_dpp v239, v33, v159 row_shr:1 row_mask:0xf bank_mask:0xf
	v_fmac_f32_dpp v240, v34, v160 row_shr:1 row_mask:0xf bank_mask:0xf
	v_fmac_f32_dpp v241, v35, v161 row_shr:1 row_mask:0xf bank_mask:0xf
	v_fmac_f32_dpp v238, v48, v158 row_shl:15 row_mask:0xf bank_mask:0xf
	v_fmac_f32_dpp v239, v49, v159 row_shl:15 row_mask:0xf bank_mask:0xf
	v_fmac_f32_dpp v240, v50, v160 row_shl:15 row_mask:0xf bank_mask:0xf
	v_fmac_f32_dpp v241, v51, v161 row_shl:15 row_mask:0xf bank_mask:0xf
; __device__ __forceinline__ unsigned cvt_pk_bf16(float lo, float hi) { unsigned r; asm volatile("v_cvt_pk_bf16_f32 %0, %1, %2" : "=v"(r) : "v"(lo), "v"(hi)); return r; }
;     __device__ __forceinline__ void operator()(const f32x4 (&acc)[2][2][4][2], const Unit& u, int wr, int wc, int fr_in, int fq_in) const {
;     ...
;                             for (int j = 0; j < 4; ++j) e[j] = __builtin_amdgcn_rcpf(1.0f + __builtin_amdgcn_exp2f(c[j] * -1.4426950408889634f));
;                             o[m] = o[m] * (c * e); }
;                         up_prev = up_cur; dn_cur = dn_next; }
;                 }
;                 if (n == 0) {
; #pragma unroll
;                     for (int m = 0; m < 4; ++m) { wlo[m].x = cvt_pk_bf16(o[m][0], o[m][1]); wlo[m].y = cvt_pk_bf16(o[m][2], o[m][3]); }
;                 } else {
; #pragma unroll
;                     for (int m = 0; m < 4; ++m) { u32x4 w; w.x = wlo[m].x; w.y = wlo[m].y; w.z = cvt_pk_bf16(o[m][0], o[m][1]); w.w = cvt_pk_bf16(o[m][2], o[m][3]);
;                         *(u32x4*)(base + off0 + (unsigned)(ai * HALF + m * 16) * (DFF * 2u)) = w; }
;                 }
;                 if (fr < 2 || fr >= 14) { const int k = fr < 2 ? fr : fr - 12;
;                     const f32x4 xv = fr < 2 ? acc[ai][0][0][n] : acc[ai][0][3][n], yv = fr < 2 ? acc[ai][1][0][n] : acc[ai][1][3][n];
;                     char* sp = sbase + (size_t)((2 * ai + wr) * 4 + k) * (DFF2 * 2) + (size_t)ch * 2;
;                     u32x2 a, b; a.x = cvt_pk_bf16(xv[0], xv[1]); a.y = cvt_pk_bf16(xv[2], xv[3]); b.x = cvt_pk_bf16(yv[0], yv[1]); b.y = cvt_pk_bf16(yv[2], yv[3]);
;                     *(u32x2*)sp = a; *(u32x2*)(sp + DFF * 2) = b; }
	v_fmac_f32_dpp v238, v32, v166 row_shl:1 row_mask:0xf bank_mask:0xf
	v_fmac_f32_dpp v239, v33, v167 row_shl:1 row_mask:0xf bank_mask:0xf
	v_fmac_f32_dpp v240, v34, v168 row_shl:1 row_mask:0xf bank_mask:0xf
	v_fmac_f32_dpp v241, v35, v169 row_shl:1 row_mask:0xf bank_mask:0xf
	v_mul_f32_e32 v242, 0xbfb8aa3b, v226
	v_mul_f32_e32 v243, 0xbfb8aa3b, v227
	v_mul_f32_e32 v244, 0xbfb8aa3b, v228
	v_mul_f32_e32 v245, 0xbfb8aa3b, v229
	v_mul_f32_e32 v246, 0xbfb8aa3b, v230
	v_mul_f32_e32 v247, 0xbfb8aa3b, v231
	v_mul_f32_e32 v248, 0xbfb8aa3b, v232
	v_mul_f32_e32 v249, 0xbfb8aa3b, v233
	v_exp_f32_e32 v242, v242
	v_exp_f32_e32 v243, v243
	v_exp_f32_e32 v244, v244
	v_exp_f32_e32 v245, v245
	v_exp_f32_e32 v246, v246
	v_exp_f32_e32 v247, v247
	v_exp_f32_e32 v248, v248
	v_exp_f32_e32 v249, v249
	v_add_f32_e32 v242, 1.0, v242
	v_add_f32_e32 v243, 1.0, v243
	v_add_f32_e32 v244, 1.0, v244
	v_add_f32_e32 v245, 1.0, v245
	v_add_f32_e32 v246, 1.0, v246
	v_add_f32_e32 v247, 1.0, v247
	v_add_f32_e32 v248, 1.0, v248
	v_add_f32_e32 v249, 1.0, v249
	v_rcp_f32_e32 v242, v242
	v_rcp_f32_e32 v243, v243
	v_rcp_f32_e32 v244, v244
	v_rcp_f32_e32 v245, v245
	v_rcp_f32_e32 v246, v246
	v_rcp_f32_e32 v247, v247
	v_rcp_f32_e32 v248, v248
	v_rcp_f32_e32 v249, v249
	v_mul_f32_e32 v242, v226, v242
	v_mul_f32_e32 v243, v227, v243
	v_mul_f32_e32 v244, v228, v244
	v_mul_f32_e32 v245, v229, v245
	v_mul_f32_e32 v246, v230, v246
	v_mul_f32_e32 v247, v231, v247
	v_mul_f32_e32 v248, v232, v248
	v_mul_f32_e32 v249, v233, v249
	v_mul_f32_e32 v174, v174, v242
	v_mul_f32_e32 v175, v175, v243
	v_mul_f32_e32 v176, v176, v244
	v_mul_f32_e32 v177, v177, v245
	v_mul_f32_e32 v178, v178, v246
	v_mul_f32_e32 v179, v179, v247
	v_mul_f32_e32 v180, v180, v248
	v_mul_f32_e32 v181, v181, v249
	v_mul_f32_e32 v242, 0xbfb8aa3b, v234
	v_mul_f32_e32 v243, 0xbfb8aa3b, v235
	v_mul_f32_e32 v244, 0xbfb8aa3b, v236
	v_mul_f32_e32 v245, 0xbfb8aa3b, v237
	v_mul_f32_e32 v246, 0xbfb8aa3b, v238
	v_mul_f32_e32 v247, 0xbfb8aa3b, v239
	v_mul_f32_e32 v248, 0xbfb8aa3b, v240
	v_mul_f32_e32 v249, 0xbfb8aa3b, v241
	v_exp_f32_e32 v242, v242
	v_exp_f32_e32 v243, v243
	v_exp_f32_e32 v244, v244
	v_exp_f32_e32 v245, v245
	v_exp_f32_e32 v246, v246
	v_exp_f32_e32 v247, v247
	v_exp_f32_e32 v248, v248
	v_exp_f32_e32 v249, v249
	v_add_f32_e32 v242, 1.0, v242
	v_add_f32_e32 v243, 1.0, v243
	v_add_f32_e32 v244, 1.0, v244
	v_add_f32_e32 v245, 1.0, v245
	v_add_f32_e32 v246, 1.0, v246
	v_add_f32_e32 v247, 1.0, v247
	v_add_f32_e32 v248, 1.0, v248
	v_add_f32_e32 v249, 1.0, v249
	v_rcp_f32_e32 v242, v242
	v_rcp_f32_e32 v243, v243
	v_rcp_f32_e32 v244, v244
	v_rcp_f32_e32 v245, v245
	v_rcp_f32_e32 v246, v246
	v_rcp_f32_e32 v247, v247
	v_rcp_f32_e32 v248, v248
	v_rcp_f32_e32 v249, v249
	v_mul_f32_e32 v242, v234, v242
	v_mul_f32_e32 v243, v235, v243
	v_mul_f32_e32 v244, v236, v244
	v_mul_f32_e32 v245, v237, v245
	v_mul_f32_e32 v246, v238, v246
	v_mul_f32_e32 v247, v239, v247
	v_mul_f32_e32 v248, v240, v248
	v_mul_f32_e32 v249, v241, v249
	v_mul_f32_e32 v186, v186, v242
	v_mul_f32_e32 v187, v187, v243
	v_mul_f32_e32 v188, v188, v244
	v_mul_f32_e32 v189, v189, v245
	v_mul_f32_e32 v190, v190, v246
	v_mul_f32_e32 v191, v191, v247
	v_mul_f32_e32 v192, v192, v248
	v_mul_f32_e32 v193, v193, v249
	v_cvt_pk_bf16_f32 v44, v174, v175
	v_cvt_pk_bf16_f32 v45, v176, v177
	v_cvt_pk_bf16_f32 v60, v178, v179
	v_cvt_pk_bf16_f32 v61, v180, v181
	v_cvt_pk_bf16_f32 v56, v186, v187
	v_cvt_pk_bf16_f32 v57, v188, v189
	v_cvt_pk_bf16_f32 v40, v190, v191
	v_cvt_pk_bf16_f32 v41, v192, v193
	ds_read_b128 v[130:133], v213 offset:512
	ds_read_b128 v[134:137], v213 offset:576
	ds_read_b128 v[138:141], v213 offset:640
	ds_read_b128 v[142:145], v213 offset:704
	ds_read_b128 v[158:161], v213 offset:768
	ds_read_b128 v[162:165], v213 offset:832
	ds_read_b128 v[166:169], v213 offset:896
	ds_read_b128 v[170:173], v213 offset:960
	v_cndmask_b32_e64 v202, v72, v76, s[12:13]
	v_cndmask_b32_e64 v203, v73, v77, s[12:13]
	v_cndmask_b32_e64 v204, v74, v78, s[12:13]
	v_cndmask_b32_e64 v205, v75, v79, s[12:13]
	v_cndmask_b32_e64 v206, v68, v64, s[12:13]
	v_cndmask_b32_e64 v207, v69, v65, s[12:13]
	v_cndmask_b32_e64 v208, v70, v66, s[12:13]
	v_cndmask_b32_e64 v209, v71, v67, s[12:13]
	v_cvt_pk_bf16_f32 v250, v202, v203
	v_cvt_pk_bf16_f32 v251, v204, v205
	v_cvt_pk_bf16_f32 v252, v206, v207
	v_cvt_pk_bf16_f32 v253, v208, v209
	s_sub_u32 s10, s10, 0x16000
	s_subb_u32 s11, s11, 0
	s_mov_b64 s[42:43], exec
	s_and_b64 exec, exec, s[22:23]
	global_store_dwordx2 v195, v[250:251], s[10:11] offset:8
	global_store_dwordx2 v197, v[252:253], s[10:11] offset:8
	s_mov_b64 exec, s[42:43]
	s_waitcnt lgkmcnt(0)
; #define DPP_UP(v) __int_as_float(__builtin_amdgcn_update_dpp(0, __float_as_int(v), 0x121, 0xf, 0xf, false))
; #define DPP_DN(v) __int_as_float(__builtin_amdgcn_update_dpp(0, __float_as_int(v), 0x12F, 0xf, 0xf, false))
;     __device__ __forceinline__ void operator()(const f32x4 (&acc)[2][2][4][2], const Unit& u, int wr, int wc, int fr_in, int fq_in) const {
;     ...
;                     const f32x4 k0 = *(const f32x4*)(fk + co + ch), k1 = *(const f32x4*)(fk + DFF2 + co + ch), k2 = *(const f32x4*)(fk + 2 * DFF2 + co + ch), bb = *(const f32x4*)(fb + co + ch);
;                     f32x4 up_prev = (f32x4){0.f, 0.f, 0.f, 0.f}, up_cur, dn_cur, dn_next;
; #pragma unroll
;                     for (int j = 0; j < 4; ++j) dn_cur[j] = DPP_DN(acc[ai][pass][0][n][j]);
; #pragma unroll
;                     for (int m = 0; m < 4; ++m) {
;                         const f32x4 xv = acc[ai][pass][m][n];
; #pragma unroll
;                         for (int j = 0; j < 4; ++j) { up_cur[j] = DPP_UP(xv[j]); dn_next[j] = (m < 3) ? DPP_DN(acc[ai][pass][m < 3 ? m + 1 : 3][n][j]) : 0.f; }
;                         const f32x4 xp = f0 ? up_prev : up_cur, xn = f15 ? dn_next : dn_cur;
;                         const f32x4 c = (k0 * xp + k1 * xv) + (k2 * xn + bb);
	v_fma_f32 v174, v134, v76, v142
	v_fma_f32 v175, v135, v77, v143
	v_fma_f32 v176, v136, v78, v144
	v_fma_f32 v177, v137, v79, v145
	v_fma_f32 v178, v134, v92, v142
	v_fma_f32 v179, v135, v93, v143
	v_fma_f32 v180, v136, v94, v144
	v_fma_f32 v181, v137, v95, v145
	v_fma_f32 v186, v134, v88, v142
	v_fma_f32 v187, v135, v89, v143
	v_fma_f32 v188, v136, v90, v144
	v_fma_f32 v189, v137, v91, v145
	v_fma_f32 v190, v134, v72, v142
	v_fma_f32 v191, v135, v73, v143
	v_fma_f32 v192, v136, v74, v144
	v_fma_f32 v193, v137, v75, v145
	v_fmac_f32_dpp v174, v76, v130 row_shr:1 row_mask:0xf bank_mask:0xf
	v_fmac_f32_dpp v175, v77, v131 row_shr:1 row_mask:0xf bank_mask:0xf
	v_fmac_f32_dpp v176, v78, v132 row_shr:1 row_mask:0xf bank_mask:0xf
	v_fmac_f32_dpp v177, v79, v133 row_shr:1 row_mask:0xf bank_mask:0xf
	v_fmac_f32_dpp v174, v76, v138 row_shl:1 row_mask:0xf bank_mask:0xf
	v_fmac_f32_dpp v175, v77, v139 row_shl:1 row_mask:0xf bank_mask:0xf
	v_fmac_f32_dpp v176, v78, v140 row_shl:1 row_mask:0xf bank_mask:0xf
	v_fmac_f32_dpp v177, v79, v141 row_shl:1 row_mask:0xf bank_mask:0xf
	v_fmac_f32_dpp v174, v92, v138 row_shr:15 row_mask:0xf bank_mask:0xf
	v_fmac_f32_dpp v175, v93, v139 row_shr:15 row_mask:0xf bank_mask:0xf
	v_fmac_f32_dpp v176, v94, v140 row_shr:15 row_mask:0xf bank_mask:0xf
	v_fmac_f32_dpp v177, v95, v141 row_shr:15 row_mask:0xf bank_mask:0xf
	v_fmac_f32_dpp v178, v92, v130 row_shr:1 row_mask:0xf bank_mask:0xf
	v_fmac_f32_dpp v179, v93, v131 row_shr:1 row_mask:0xf bank_mask:0xf
	v_fmac_f32_dpp v180, v94, v132 row_shr:1 row_mask:0xf bank_mask:0xf
	v_fmac_f32_dpp v181, v95, v133 row_shr:1 row_mask:0xf bank_mask:0xf
	v_fmac_f32_dpp v178, v76, v130 row_shl:15 row_mask:0xf bank_mask:0xf
	v_fmac_f32_dpp v179, v77, v131 row_shl:15 row_mask:0xf bank_mask:0xf
	v_fmac_f32_dpp v180, v78, v132 row_shl:15 row_mask:0xf bank_mask:0xf
	v_fmac_f32_dpp v181, v79, v133 row_shl:15 row_mask:0xf bank_mask:0xf
	v_fmac_f32_dpp v178, v92, v138 row_shl:1 row_mask:0xf bank_mask:0xf
	v_fmac_f32_dpp v179, v93, v139 row_shl:1 row_mask:0xf bank_mask:0xf
	v_fmac_f32_dpp v180, v94, v140 row_shl:1 row_mask:0xf bank_mask:0xf
	v_fmac_f32_dpp v181, v95, v141 row_shl:1 row_mask:0xf bank_mask:0xf
	v_fmac_f32_dpp v178, v88, v138 row_shr:15 row_mask:0xf bank_mask:0xf
	v_fmac_f32_dpp v179, v89, v139 row_shr:15 row_mask:0xf bank_mask:0xf
	v_fmac_f32_dpp v180, v90, v140 row_shr:15 row_mask:0xf bank_mask:0xf
	v_fmac_f32_dpp v181, v91, v141 row_shr:15 row_mask:0xf bank_mask:0xf
	v_fmac_f32_dpp v186, v88, v130 row_shr:1 row_mask:0xf bank_mask:0xf
	v_fmac_f32_dpp v187, v89, v131 row_shr:1 row_mask:0xf bank_mask:0xf
	v_fmac_f32_dpp v188, v90, v132 row_shr:1 row_mask:0xf bank_mask:0xf
	v_fmac_f32_dpp v189, v91, v133 row_shr:1 row_mask:0xf bank_mask:0xf
	v_fmac_f32_dpp v186, v92, v130 row_shl:15 row_mask:0xf bank_mask:0xf
	v_fmac_f32_dpp v187, v93, v131 row_shl:15 row_mask:0xf bank_mask:0xf
	v_fmac_f32_dpp v188, v94, v132 row_shl:15 row_mask:0xf bank_mask:0xf
	v_fmac_f32_dpp v189, v95, v133 row_shl:15 row_mask:0xf bank_mask:0xf
	v_fmac_f32_dpp v186, v88, v138 row_shl:1 row_mask:0xf bank_mask:0xf
	v_fmac_f32_dpp v187, v89, v139 row_shl:1 row_mask:0xf bank_mask:0xf
	v_fmac_f32_dpp v188, v90, v140 row_shl:1 row_mask:0xf bank_mask:0xf
	v_fmac_f32_dpp v189, v91, v141 row_shl:1 row_mask:0xf bank_mask:0xf
	v_fmac_f32_dpp v186, v72, v138 row_shr:15 row_mask:0xf bank_mask:0xf
	v_fmac_f32_dpp v187, v73, v139 row_shr:15 row_mask:0xf bank_mask:0xf
	v_fmac_f32_dpp v188, v74, v140 row_shr:15 row_mask:0xf bank_mask:0xf
	v_fmac_f32_dpp v189, v75, v141 row_shr:15 row_mask:0xf bank_mask:0xf
	v_fmac_f32_dpp v190, v72, v130 row_shr:1 row_mask:0xf bank_mask:0xf
	v_fmac_f32_dpp v191, v73, v131 row_shr:1 row_mask:0xf bank_mask:0xf
	v_fmac_f32_dpp v192, v74, v132 row_shr:1 row_mask:0xf bank_mask:0xf
	v_fmac_f32_dpp v193, v75, v133 row_shr:1 row_mask:0xf bank_mask:0xf
	v_fmac_f32_dpp v190, v88, v130 row_shl:15 row_mask:0xf bank_mask:0xf
	v_fmac_f32_dpp v191, v89, v131 row_shl:15 row_mask:0xf bank_mask:0xf
	v_fmac_f32_dpp v192, v90, v132 row_shl:15 row_mask:0xf bank_mask:0xf
	v_fmac_f32_dpp v193, v91, v133 row_shl:15 row_mask:0xf bank_mask:0xf
	v_fmac_f32_dpp v190, v72, v138 row_shl:1 row_mask:0xf bank_mask:0xf
	v_fmac_f32_dpp v191, v73, v139 row_shl:1 row_mask:0xf bank_mask:0xf
	v_fmac_f32_dpp v192, v74, v140 row_shl:1 row_mask:0xf bank_mask:0xf
	v_fmac_f32_dpp v193, v75, v141 row_shl:1 row_mask:0xf bank_mask:0xf
	v_fma_f32 v226, v162, v64, v170
	v_fma_f32 v227, v163, v65, v171
	v_fma_f32 v228, v164, v66, v172
	v_fma_f32 v229, v165, v67, v173
	v_fma_f32 v230, v162, v84, v170
	v_fma_f32 v231, v163, v85, v171
	v_fma_f32 v232, v164, v86, v172
	v_fma_f32 v233, v165, v87, v173
	v_fma_f32 v234, v162, v80, v170
	v_fma_f32 v235, v163, v81, v171
	v_fma_f32 v236, v164, v82, v172
	v_fma_f32 v237, v165, v83, v173
	v_fma_f32 v238, v162, v68, v170
	v_fma_f32 v239, v163, v69, v171
	v_fma_f32 v240, v164, v70, v172
	v_fma_f32 v241, v165, v71, v173
	v_fmac_f32_dpp v226, v64, v158 row_shr:1 row_mask:0xf bank_mask:0xf
	v_fmac_f32_dpp v227, v65, v159 row_shr:1 row_mask:0xf bank_mask:0xf
	v_fmac_f32_dpp v228, v66, v160 row_shr:1 row_mask:0xf bank_mask:0xf
	v_fmac_f32_dpp v229, v67, v161 row_shr:1 row_mask:0xf bank_mask:0xf
	v_fmac_f32_dpp v226, v64, v166 row_shl:1 row_mask:0xf bank_mask:0xf
	v_fmac_f32_dpp v227, v65, v167 row_shl:1 row_mask:0xf bank_mask:0xf
	v_fmac_f32_dpp v228, v66, v168 row_shl:1 row_mask:0xf bank_mask:0xf
	v_fmac_f32_dpp v229, v67, v169 row_shl:1 row_mask:0xf bank_mask:0xf
	v_fmac_f32_dpp v226, v84, v166 row_shr:15 row_mask:0xf bank_mask:0xf
	v_fmac_f32_dpp v227, v85, v167 row_shr:15 row_mask:0xf bank_mask:0xf
; #define DPP_UP(v) __int_as_float(__builtin_amdgcn_update_dpp(0, __float_as_int(v), 0x121, 0xf, 0xf, false))
; #define DPP_DN(v) __int_as_float(__builtin_amdgcn_update_dpp(0, __float_as_int(v), 0x12F, 0xf, 0xf, false))
;     __device__ __forceinline__ void operator()(const f32x4 (&acc)[2][2][4][2], const Unit& u, int wr, int wc, int fr_in, int fq_in) const {
;     ...
;                         for (int j = 0; j < 4; ++j) { up_cur[j] = DPP_UP(xv[j]); dn_next[j] = (m < 3) ? DPP_DN(acc[ai][pass][m < 3 ? m + 1 : 3][n][j]) : 0.f; }
;                         const f32x4 xp = f0 ? up_prev : up_cur, xn = f15 ? dn_next : dn_cur;
;                         const f32x4 c = (k0 * xp + k1 * xv) + (k2 * xn + bb);
;                         if (pass == 0) o[m] = c;
;                         else { f32x4 e;
; #pragma unroll
;                             for (int j = 0; j < 4; ++j) e[j] = __builtin_amdgcn_rcpf(1.0f + __builtin_amdgcn_exp2f(c[j] * -1.4426950408889634f));
;                             o[m] = o[m] * (c * e); }
	v_fmac_f32_dpp v228, v86, v168 row_shr:15 row_mask:0xf bank_mask:0xf
	v_fmac_f32_dpp v229, v87, v169 row_shr:15 row_mask:0xf bank_mask:0xf
	v_fmac_f32_dpp v230, v84, v158 row_shr:1 row_mask:0xf bank_mask:0xf
	v_fmac_f32_dpp v231, v85, v159 row_shr:1 row_mask:0xf bank_mask:0xf
	v_fmac_f32_dpp v232, v86, v160 row_shr:1 row_mask:0xf bank_mask:0xf
	v_fmac_f32_dpp v233, v87, v161 row_shr:1 row_mask:0xf bank_mask:0xf
	v_fmac_f32_dpp v230, v64, v158 row_shl:15 row_mask:0xf bank_mask:0xf
	v_fmac_f32_dpp v231, v65, v159 row_shl:15 row_mask:0xf bank_mask:0xf
	v_fmac_f32_dpp v232, v66, v160 row_shl:15 row_mask:0xf bank_mask:0xf
	v_fmac_f32_dpp v233, v67, v161 row_shl:15 row_mask:0xf bank_mask:0xf
	v_fmac_f32_dpp v230, v84, v166 row_shl:1 row_mask:0xf bank_mask:0xf
	v_fmac_f32_dpp v231, v85, v167 row_shl:1 row_mask:0xf bank_mask:0xf
	v_fmac_f32_dpp v232, v86, v168 row_shl:1 row_mask:0xf bank_mask:0xf
	v_fmac_f32_dpp v233, v87, v169 row_shl:1 row_mask:0xf bank_mask:0xf
	v_fmac_f32_dpp v230, v80, v166 row_shr:15 row_mask:0xf bank_mask:0xf
	v_fmac_f32_dpp v231, v81, v167 row_shr:15 row_mask:0xf bank_mask:0xf
	v_fmac_f32_dpp v232, v82, v168 row_shr:15 row_mask:0xf bank_mask:0xf
	v_fmac_f32_dpp v233, v83, v169 row_shr:15 row_mask:0xf bank_mask:0xf
	v_fmac_f32_dpp v234, v80, v158 row_shr:1 row_mask:0xf bank_mask:0xf
	v_fmac_f32_dpp v235, v81, v159 row_shr:1 row_mask:0xf bank_mask:0xf
	v_fmac_f32_dpp v236, v82, v160 row_shr:1 row_mask:0xf bank_mask:0xf
	v_fmac_f32_dpp v237, v83, v161 row_shr:1 row_mask:0xf bank_mask:0xf
	v_fmac_f32_dpp v234, v84, v158 row_shl:15 row_mask:0xf bank_mask:0xf
	v_fmac_f32_dpp v235, v85, v159 row_shl:15 row_mask:0xf bank_mask:0xf
	v_fmac_f32_dpp v236, v86, v160 row_shl:15 row_mask:0xf bank_mask:0xf
	v_fmac_f32_dpp v237, v87, v161 row_shl:15 row_mask:0xf bank_mask:0xf
	v_fmac_f32_dpp v234, v80, v166 row_shl:1 row_mask:0xf bank_mask:0xf
	v_fmac_f32_dpp v235, v81, v167 row_shl:1 row_mask:0xf bank_mask:0xf
	v_fmac_f32_dpp v236, v82, v168 row_shl:1 row_mask:0xf bank_mask:0xf
	v_fmac_f32_dpp v237, v83, v169 row_shl:1 row_mask:0xf bank_mask:0xf
	v_fmac_f32_dpp v234, v68, v166 row_shr:15 row_mask:0xf bank_mask:0xf
	v_fmac_f32_dpp v235, v69, v167 row_shr:15 row_mask:0xf bank_mask:0xf
	v_fmac_f32_dpp v236, v70, v168 row_shr:15 row_mask:0xf bank_mask:0xf
	v_fmac_f32_dpp v237, v71, v169 row_shr:15 row_mask:0xf bank_mask:0xf
	v_fmac_f32_dpp v238, v68, v158 row_shr:1 row_mask:0xf bank_mask:0xf
	v_fmac_f32_dpp v239, v69, v159 row_shr:1 row_mask:0xf bank_mask:0xf
	v_fmac_f32_dpp v240, v70, v160 row_shr:1 row_mask:0xf bank_mask:0xf
	v_fmac_f32_dpp v241, v71, v161 row_shr:1 row_mask:0xf bank_mask:0xf
	v_fmac_f32_dpp v238, v80, v158 row_shl:15 row_mask:0xf bank_mask:0xf
	v_fmac_f32_dpp v239, v81, v159 row_shl:15 row_mask:0xf bank_mask:0xf
	v_fmac_f32_dpp v240, v82, v160 row_shl:15 row_mask:0xf bank_mask:0xf
	v_fmac_f32_dpp v241, v83, v161 row_shl:15 row_mask:0xf bank_mask:0xf
	v_fmac_f32_dpp v238, v68, v166 row_shl:1 row_mask:0xf bank_mask:0xf
	v_fmac_f32_dpp v239, v69, v167 row_shl:1 row_mask:0xf bank_mask:0xf
	v_fmac_f32_dpp v240, v70, v168 row_shl:1 row_mask:0xf bank_mask:0xf
	v_fmac_f32_dpp v241, v71, v169 row_shl:1 row_mask:0xf bank_mask:0xf
	v_mul_f32_e32 v242, 0xbfb8aa3b, v226
	v_mul_f32_e32 v243, 0xbfb8aa3b, v227
	v_mul_f32_e32 v244, 0xbfb8aa3b, v228
	v_mul_f32_e32 v245, 0xbfb8aa3b, v229
	v_mul_f32_e32 v246, 0xbfb8aa3b, v230
	v_mul_f32_e32 v247, 0xbfb8aa3b, v231
	v_mul_f32_e32 v248, 0xbfb8aa3b, v232
	v_mul_f32_e32 v249, 0xbfb8aa3b, v233
	v_exp_f32_e32 v242, v242
	v_exp_f32_e32 v243, v243
	v_exp_f32_e32 v244, v244
	v_exp_f32_e32 v245, v245
	v_exp_f32_e32 v246, v246
	v_exp_f32_e32 v247, v247
	v_exp_f32_e32 v248, v248
	v_exp_f32_e32 v249, v249
	v_add_f32_e32 v242, 1.0, v242
	v_add_f32_e32 v243, 1.0, v243
	v_add_f32_e32 v244, 1.0, v244
	v_add_f32_e32 v245, 1.0, v245
	v_add_f32_e32 v246, 1.0, v246
	v_add_f32_e32 v247, 1.0, v247
	v_add_f32_e32 v248, 1.0, v248
	v_add_f32_e32 v249, 1.0, v249
	v_rcp_f32_e32 v242, v242
	v_rcp_f32_e32 v243, v243
	v_rcp_f32_e32 v244, v244
	v_rcp_f32_e32 v245, v245
	v_rcp_f32_e32 v246, v246
	v_rcp_f32_e32 v247, v247
	v_rcp_f32_e32 v248, v248
	v_rcp_f32_e32 v249, v249
	v_mul_f32_e32 v242, v226, v242
	v_mul_f32_e32 v243, v227, v243
	v_mul_f32_e32 v244, v228, v244
	v_mul_f32_e32 v245, v229, v245
	v_mul_f32_e32 v246, v230, v246
	v_mul_f32_e32 v247, v231, v247
	v_mul_f32_e32 v248, v232, v248
	v_mul_f32_e32 v249, v233, v249
	v_mul_f32_e32 v174, v174, v242
	v_mul_f32_e32 v175, v175, v243
	v_mul_f32_e32 v176, v176, v244
	v_mul_f32_e32 v177, v177, v245
	v_mul_f32_e32 v178, v178, v246
	v_mul_f32_e32 v179, v179, v247
	v_mul_f32_e32 v180, v180, v248
	v_mul_f32_e32 v181, v181, v249
	v_mul_f32_e32 v242, 0xbfb8aa3b, v234
	v_mul_f32_e32 v243, 0xbfb8aa3b, v235
	v_mul_f32_e32 v244, 0xbfb8aa3b, v236
	v_mul_f32_e32 v245, 0xbfb8aa3b, v237
	v_mul_f32_e32 v246, 0xbfb8aa3b, v238
	v_mul_f32_e32 v247, 0xbfb8aa3b, v239
	v_mul_f32_e32 v248, 0xbfb8aa3b, v240
	v_mul_f32_e32 v249, 0xbfb8aa3b, v241
	v_exp_f32_e32 v242, v242
	v_exp_f32_e32 v243, v243
	v_exp_f32_e32 v244, v244
	v_exp_f32_e32 v245, v245
	v_exp_f32_e32 v246, v246
	v_exp_f32_e32 v247, v247
	v_exp_f32_e32 v248, v248
	v_exp_f32_e32 v249, v249
	v_add_f32_e32 v242, 1.0, v242
	v_add_f32_e32 v243, 1.0, v243
	v_add_f32_e32 v244, 1.0, v244
	v_add_f32_e32 v245, 1.0, v245
	v_add_f32_e32 v246, 1.0, v246
	v_add_f32_e32 v247, 1.0, v247
	v_add_f32_e32 v248, 1.0, v248
	v_add_f32_e32 v249, 1.0, v249
	v_rcp_f32_e32 v242, v242
	v_rcp_f32_e32 v243, v243
	v_rcp_f32_e32 v244, v244
	v_rcp_f32_e32 v245, v245
	v_rcp_f32_e32 v246, v246
	v_rcp_f32_e32 v247, v247
	v_rcp_f32_e32 v248, v248
	v_rcp_f32_e32 v249, v249
; __device__ __forceinline__ unsigned cvt_pk_bf16(float lo, float hi) { unsigned r; asm volatile("v_cvt_pk_bf16_f32 %0, %1, %2" : "=v"(r) : "v"(lo), "v"(hi)); return r; }
;     __device__ __forceinline__ void operator()(const f32x4 (&acc)[2][2][4][2], const Unit& u, int wr, int wc, int fr_in, int fq_in) const {
;     ...
;                             for (int j = 0; j < 4; ++j) e[j] = __builtin_amdgcn_rcpf(1.0f + __builtin_amdgcn_exp2f(c[j] * -1.4426950408889634f));
;                             o[m] = o[m] * (c * e); }
;                         up_prev = up_cur; dn_cur = dn_next; }
;                 }
;                 if (n == 0) {
; #pragma unroll
;                     for (int m = 0; m < 4; ++m) { wlo[m].x = cvt_pk_bf16(o[m][0], o[m][1]); wlo[m].y = cvt_pk_bf16(o[m][2], o[m][3]); }
;                 } else {
; #pragma unroll
;                     for (int m = 0; m < 4; ++m) { u32x4 w; w.x = wlo[m].x; w.y = wlo[m].y; w.z = cvt_pk_bf16(o[m][0], o[m][1]); w.w = cvt_pk_bf16(o[m][2], o[m][3]);
;                         *(u32x4*)(base + off0 + (unsigned)(ai * HALF + m * 16) * (DFF * 2u)) = w; }
;                 }
;                 if (fr < 2 || fr >= 14) { const int k = fr < 2 ? fr : fr - 12;
;                     const f32x4 xv = fr < 2 ? acc[ai][0][0][n] : acc[ai][0][3][n], yv = fr < 2 ? acc[ai][1][0][n] : acc[ai][1][3][n];
;                     char* sp = sbase + (size_t)((2 * ai + wr) * 4 + k) * (DFF2 * 2) + (size_t)ch * 2;
;                     u32x2 a, b; a.x = cvt_pk_bf16(xv[0], xv[1]); a.y = cvt_pk_bf16(xv[2], xv[3]); b.x = cvt_pk_bf16(yv[0], yv[1]); b.y = cvt_pk_bf16(yv[2], yv[3]);
;                     *(u32x2*)sp = a; *(u32x2*)(sp + DFF * 2) = b; }
	v_mul_f32_e32 v242, v234, v242
	v_mul_f32_e32 v243, v235, v243
	v_mul_f32_e32 v244, v236, v244
	v_mul_f32_e32 v245, v237, v245
	v_mul_f32_e32 v246, v238, v246
	v_mul_f32_e32 v247, v239, v247
	v_mul_f32_e32 v248, v240, v248
	v_mul_f32_e32 v249, v241, v249
	v_mul_f32_e32 v186, v186, v242
	v_mul_f32_e32 v187, v187, v243
	v_mul_f32_e32 v188, v188, v244
	v_mul_f32_e32 v189, v189, v245
	v_mul_f32_e32 v190, v190, v246
	v_mul_f32_e32 v191, v191, v247
	v_mul_f32_e32 v192, v192, v248
	v_mul_f32_e32 v193, v193, v249
	v_cvt_pk_bf16_f32 v112, v174, v175
	v_cvt_pk_bf16_f32 v113, v176, v177
	v_cvt_pk_bf16_f32 v128, v178, v179
	v_cvt_pk_bf16_f32 v129, v180, v181
	v_cvt_pk_bf16_f32 v124, v186, v187
	v_cvt_pk_bf16_f32 v125, v188, v189
	v_cvt_pk_bf16_f32 v108, v190, v191
	v_cvt_pk_bf16_f32 v109, v192, v193
	global_store_dwordx4 v194, v[110:113], s[6:7]
	s_add_u32 s0, s6, 0x16000
	s_addc_u32 s1, s7, 0
	global_store_dwordx4 v194, v[126:129], s[0:1]
	s_add_u32 s0, s6, 0x2c000
	s_addc_u32 s1, s7, 0
	global_store_dwordx4 v194, v[122:125], s[0:1]
	s_add_u32 s0, s6, 0x42000
	s_addc_u32 s1, s7, 0
	global_store_dwordx4 v194, v[106:109], s[0:1]
	v_cndmask_b32_e64 v202, v4, v0, s[12:13]
	v_cndmask_b32_e64 v203, v5, v1, s[12:13]
	v_cndmask_b32_e64 v204, v6, v2, s[12:13]
	v_cndmask_b32_e64 v205, v7, v3, s[12:13]
	v_cndmask_b32_e64 v206, v12, v8, s[12:13]
	v_cndmask_b32_e64 v207, v13, v9, s[12:13]
	v_cndmask_b32_e64 v208, v14, v10, s[12:13]
	v_cndmask_b32_e64 v209, v15, v11, s[12:13]
	v_cvt_pk_bf16_f32 v250, v202, v203
	v_cvt_pk_bf16_f32 v251, v204, v205
	v_cvt_pk_bf16_f32 v252, v206, v207
	v_cvt_pk_bf16_f32 v253, v208, v209
	s_add_u32 s10, s10, 0x16000
	s_addc_u32 s11, s11, 0
	s_mov_b64 s[42:43], exec
	s_and_b64 exec, exec, s[22:23]
	global_store_dwordx2 v195, v[250:251], s[10:11] offset:8
	global_store_dwordx2 v197, v[252:253], s[10:11] offset:8
	s_mov_b64 exec, s[42:43]
	v_fma_f32 v174, v134, v0, v142
	v_fma_f32 v175, v135, v1, v143
	v_fma_f32 v176, v136, v2, v144
	v_fma_f32 v177, v137, v3, v145
	v_fma_f32 v178, v134, v28, v142
	v_fma_f32 v179, v135, v29, v143
	v_fma_f32 v180, v136, v30, v144
	v_fma_f32 v181, v137, v31, v145
	v_fma_f32 v186, v134, v24, v142
	v_fma_f32 v187, v135, v25, v143
	v_fma_f32 v188, v136, v26, v144
	v_fma_f32 v189, v137, v27, v145
	v_fma_f32 v190, v134, v4, v142
	v_fma_f32 v191, v135, v5, v143
	v_fma_f32 v192, v136, v6, v144
	v_fma_f32 v193, v137, v7, v145
	v_fmac_f32_dpp v174, v0, v130 row_shr:1 row_mask:0xf bank_mask:0xf
	v_fmac_f32_dpp v175, v1, v131 row_shr:1 row_mask:0xf bank_mask:0xf
	v_fmac_f32_dpp v176, v2, v132 row_shr:1 row_mask:0xf bank_mask:0xf
	v_fmac_f32_dpp v177, v3, v133 row_shr:1 row_mask:0xf bank_mask:0xf
	v_fmac_f32_dpp v174, v0, v138 row_shl:1 row_mask:0xf bank_mask:0xf
	v_fmac_f32_dpp v175, v1, v139 row_shl:1 row_mask:0xf bank_mask:0xf
	v_fmac_f32_dpp v176, v2, v140 row_shl:1 row_mask:0xf bank_mask:0xf
	v_fmac_f32_dpp v177, v3, v141 row_shl:1 row_mask:0xf bank_mask:0xf
	v_fmac_f32_dpp v174, v28, v138 row_shr:15 row_mask:0xf bank_mask:0xf
	v_fmac_f32_dpp v175, v29, v139 row_shr:15 row_mask:0xf bank_mask:0xf
	v_fmac_f32_dpp v176, v30, v140 row_shr:15 row_mask:0xf bank_mask:0xf
	v_fmac_f32_dpp v177, v31, v141 row_shr:15 row_mask:0xf bank_mask:0xf
	v_fmac_f32_dpp v178, v28, v130 row_shr:1 row_mask:0xf bank_mask:0xf
	v_fmac_f32_dpp v179, v29, v131 row_shr:1 row_mask:0xf bank_mask:0xf
	v_fmac_f32_dpp v180, v30, v132 row_shr:1 row_mask:0xf bank_mask:0xf
	v_fmac_f32_dpp v181, v31, v133 row_shr:1 row_mask:0xf bank_mask:0xf
	v_fmac_f32_dpp v178, v0, v130 row_shl:15 row_mask:0xf bank_mask:0xf
	v_fmac_f32_dpp v179, v1, v131 row_shl:15 row_mask:0xf bank_mask:0xf
	v_fmac_f32_dpp v180, v2, v132 row_shl:15 row_mask:0xf bank_mask:0xf
	v_fmac_f32_dpp v181, v3, v133 row_shl:15 row_mask:0xf bank_mask:0xf
	v_fmac_f32_dpp v178, v28, v138 row_shl:1 row_mask:0xf bank_mask:0xf
	v_fmac_f32_dpp v179, v29, v139 row_shl:1 row_mask:0xf bank_mask:0xf
	v_fmac_f32_dpp v180, v30, v140 row_shl:1 row_mask:0xf bank_mask:0xf
	v_fmac_f32_dpp v181, v31, v141 row_shl:1 row_mask:0xf bank_mask:0xf
	v_fmac_f32_dpp v178, v24, v138 row_shr:15 row_mask:0xf bank_mask:0xf
	v_fmac_f32_dpp v179, v25, v139 row_shr:15 row_mask:0xf bank_mask:0xf
	v_fmac_f32_dpp v180, v26, v140 row_shr:15 row_mask:0xf bank_mask:0xf
	v_fmac_f32_dpp v181, v27, v141 row_shr:15 row_mask:0xf bank_mask:0xf
	v_fmac_f32_dpp v186, v24, v130 row_shr:1 row_mask:0xf bank_mask:0xf
	v_fmac_f32_dpp v187, v25, v131 row_shr:1 row_mask:0xf bank_mask:0xf
	v_fmac_f32_dpp v188, v26, v132 row_shr:1 row_mask:0xf bank_mask:0xf
	v_fmac_f32_dpp v189, v27, v133 row_shr:1 row_mask:0xf bank_mask:0xf
	v_fmac_f32_dpp v186, v28, v130 row_shl:15 row_mask:0xf bank_mask:0xf
	v_fmac_f32_dpp v187, v29, v131 row_shl:15 row_mask:0xf bank_mask:0xf
	v_fmac_f32_dpp v188, v30, v132 row_shl:15 row_mask:0xf bank_mask:0xf
	v_fmac_f32_dpp v189, v31, v133 row_shl:15 row_mask:0xf bank_mask:0xf
	v_fmac_f32_dpp v186, v24, v138 row_shl:1 row_mask:0xf bank_mask:0xf
	v_fmac_f32_dpp v187, v25, v139 row_shl:1 row_mask:0xf bank_mask:0xf
	v_fmac_f32_dpp v188, v26, v140 row_shl:1 row_mask:0xf bank_mask:0xf
	v_fmac_f32_dpp v189, v27, v141 row_shl:1 row_mask:0xf bank_mask:0xf
	v_fmac_f32_dpp v186, v4, v138 row_shr:15 row_mask:0xf bank_mask:0xf
	v_fmac_f32_dpp v187, v5, v139 row_shr:15 row_mask:0xf bank_mask:0xf
	v_fmac_f32_dpp v188, v6, v140 row_shr:15 row_mask:0xf bank_mask:0xf
	v_fmac_f32_dpp v189, v7, v141 row_shr:15 row_mask:0xf bank_mask:0xf
	v_fmac_f32_dpp v190, v4, v130 row_shr:1 row_mask:0xf bank_mask:0xf
	v_fmac_f32_dpp v191, v5, v131 row_shr:1 row_mask:0xf bank_mask:0xf
	v_fmac_f32_dpp v192, v6, v132 row_shr:1 row_mask:0xf bank_mask:0xf
; #define DPP_UP(v) __int_as_float(__builtin_amdgcn_update_dpp(0, __float_as_int(v), 0x121, 0xf, 0xf, false))
; #define DPP_DN(v) __int_as_float(__builtin_amdgcn_update_dpp(0, __float_as_int(v), 0x12F, 0xf, 0xf, false))
;     __device__ __forceinline__ void operator()(const f32x4 (&acc)[2][2][4][2], const Unit& u, int wr, int wc, int fr_in, int fq_in) const {
;     ...
;                     const f32x4 k0 = *(const f32x4*)(fk + co + ch), k1 = *(const f32x4*)(fk + DFF2 + co + ch), k2 = *(const f32x4*)(fk + 2 * DFF2 + co + ch), bb = *(const f32x4*)(fb + co + ch);
;                     f32x4 up_prev = (f32x4){0.f, 0.f, 0.f, 0.f}, up_cur, dn_cur, dn_next;
; #pragma unroll
;                     for (int j = 0; j < 4; ++j) dn_cur[j] = DPP_DN(acc[ai][pass][0][n][j]);
; #pragma unroll
;                     for (int m = 0; m < 4; ++m) {
;                         const f32x4 xv = acc[ai][pass][m][n];
; #pragma unroll
;                         for (int j = 0; j < 4; ++j) { up_cur[j] = DPP_UP(xv[j]); dn_next[j] = (m < 3) ? DPP_DN(acc[ai][pass][m < 3 ? m + 1 : 3][n][j]) : 0.f; }
;                         const f32x4 xp = f0 ? up_prev : up_cur, xn = f15 ? dn_next : dn_cur;
;                         const f32x4 c = (k0 * xp + k1 * xv) + (k2 * xn + bb);
	v_fmac_f32_dpp v193, v7, v133 row_shr:1 row_mask:0xf bank_mask:0xf
	v_fmac_f32_dpp v190, v24, v130 row_shl:15 row_mask:0xf bank_mask:0xf
	v_fmac_f32_dpp v191, v25, v131 row_shl:15 row_mask:0xf bank_mask:0xf
	v_fmac_f32_dpp v192, v26, v132 row_shl:15 row_mask:0xf bank_mask:0xf
	v_fmac_f32_dpp v193, v27, v133 row_shl:15 row_mask:0xf bank_mask:0xf
	v_fmac_f32_dpp v190, v4, v138 row_shl:1 row_mask:0xf bank_mask:0xf
	v_fmac_f32_dpp v191, v5, v139 row_shl:1 row_mask:0xf bank_mask:0xf
	v_fmac_f32_dpp v192, v6, v140 row_shl:1 row_mask:0xf bank_mask:0xf
	v_fmac_f32_dpp v193, v7, v141 row_shl:1 row_mask:0xf bank_mask:0xf
	v_fma_f32 v226, v162, v8, v170
	v_fma_f32 v227, v163, v9, v171
	v_fma_f32 v228, v164, v10, v172
	v_fma_f32 v229, v165, v11, v173
	v_fma_f32 v230, v162, v20, v170
	v_fma_f32 v231, v163, v21, v171
	v_fma_f32 v232, v164, v22, v172
	v_fma_f32 v233, v165, v23, v173
	v_fma_f32 v234, v162, v16, v170
	v_fma_f32 v235, v163, v17, v171
	v_fma_f32 v236, v164, v18, v172
	v_fma_f32 v237, v165, v19, v173
	v_fma_f32 v238, v162, v12, v170
	v_fma_f32 v239, v163, v13, v171
	v_fma_f32 v240, v164, v14, v172
	v_fma_f32 v241, v165, v15, v173
	v_fmac_f32_dpp v226, v8, v158 row_shr:1 row_mask:0xf bank_mask:0xf
	v_fmac_f32_dpp v227, v9, v159 row_shr:1 row_mask:0xf bank_mask:0xf
	v_fmac_f32_dpp v228, v10, v160 row_shr:1 row_mask:0xf bank_mask:0xf
	v_fmac_f32_dpp v229, v11, v161 row_shr:1 row_mask:0xf bank_mask:0xf
	v_fmac_f32_dpp v226, v8, v166 row_shl:1 row_mask:0xf bank_mask:0xf
	v_fmac_f32_dpp v227, v9, v167 row_shl:1 row_mask:0xf bank_mask:0xf
	v_fmac_f32_dpp v228, v10, v168 row_shl:1 row_mask:0xf bank_mask:0xf
	v_fmac_f32_dpp v229, v11, v169 row_shl:1 row_mask:0xf bank_mask:0xf
	v_fmac_f32_dpp v226, v20, v166 row_shr:15 row_mask:0xf bank_mask:0xf
	v_fmac_f32_dpp v227, v21, v167 row_shr:15 row_mask:0xf bank_mask:0xf
	v_fmac_f32_dpp v228, v22, v168 row_shr:15 row_mask:0xf bank_mask:0xf
	v_fmac_f32_dpp v229, v23, v169 row_shr:15 row_mask:0xf bank_mask:0xf
	v_fmac_f32_dpp v230, v20, v158 row_shr:1 row_mask:0xf bank_mask:0xf
	v_fmac_f32_dpp v231, v21, v159 row_shr:1 row_mask:0xf bank_mask:0xf
	v_fmac_f32_dpp v232, v22, v160 row_shr:1 row_mask:0xf bank_mask:0xf
	v_fmac_f32_dpp v233, v23, v161 row_shr:1 row_mask:0xf bank_mask:0xf
	v_fmac_f32_dpp v230, v8, v158 row_shl:15 row_mask:0xf bank_mask:0xf
	v_fmac_f32_dpp v231, v9, v159 row_shl:15 row_mask:0xf bank_mask:0xf
	v_fmac_f32_dpp v232, v10, v160 row_shl:15 row_mask:0xf bank_mask:0xf
	v_fmac_f32_dpp v233, v11, v161 row_shl:15 row_mask:0xf bank_mask:0xf
	v_fmac_f32_dpp v230, v20, v166 row_shl:1 row_mask:0xf bank_mask:0xf
	v_fmac_f32_dpp v231, v21, v167 row_shl:1 row_mask:0xf bank_mask:0xf
	v_fmac_f32_dpp v232, v22, v168 row_shl:1 row_mask:0xf bank_mask:0xf
	v_fmac_f32_dpp v233, v23, v169 row_shl:1 row_mask:0xf bank_mask:0xf
	v_fmac_f32_dpp v230, v16, v166 row_shr:15 row_mask:0xf bank_mask:0xf
	v_fmac_f32_dpp v231, v17, v167 row_shr:15 row_mask:0xf bank_mask:0xf
	v_fmac_f32_dpp v232, v18, v168 row_shr:15 row_mask:0xf bank_mask:0xf
	v_fmac_f32_dpp v233, v19, v169 row_shr:15 row_mask:0xf bank_mask:0xf
	v_fmac_f32_dpp v234, v16, v158 row_shr:1 row_mask:0xf bank_mask:0xf
	v_fmac_f32_dpp v235, v17, v159 row_shr:1 row_mask:0xf bank_mask:0xf
	v_fmac_f32_dpp v236, v18, v160 row_shr:1 row_mask:0xf bank_mask:0xf
	v_fmac_f32_dpp v237, v19, v161 row_shr:1 row_mask:0xf bank_mask:0xf
	v_fmac_f32_dpp v234, v20, v158 row_shl:15 row_mask:0xf bank_mask:0xf
	v_fmac_f32_dpp v235, v21, v159 row_shl:15 row_mask:0xf bank_mask:0xf
	v_fmac_f32_dpp v236, v22, v160 row_shl:15 row_mask:0xf bank_mask:0xf
	v_fmac_f32_dpp v237, v23, v161 row_shl:15 row_mask:0xf bank_mask:0xf
	v_fmac_f32_dpp v234, v16, v166 row_shl:1 row_mask:0xf bank_mask:0xf
	v_fmac_f32_dpp v235, v17, v167 row_shl:1 row_mask:0xf bank_mask:0xf
	v_fmac_f32_dpp v236, v18, v168 row_shl:1 row_mask:0xf bank_mask:0xf
	v_fmac_f32_dpp v237, v19, v169 row_shl:1 row_mask:0xf bank_mask:0xf
	v_fmac_f32_dpp v234, v12, v166 row_shr:15 row_mask:0xf bank_mask:0xf
	v_fmac_f32_dpp v235, v13, v167 row_shr:15 row_mask:0xf bank_mask:0xf
	v_fmac_f32_dpp v236, v14, v168 row_shr:15 row_mask:0xf bank_mask:0xf
	v_fmac_f32_dpp v237, v15, v169 row_shr:15 row_mask:0xf bank_mask:0xf
	v_fmac_f32_dpp v238, v12, v158 row_shr:1 row_mask:0xf bank_mask:0xf
	v_fmac_f32_dpp v239, v13, v159 row_shr:1 row_mask:0xf bank_mask:0xf
	v_fmac_f32_dpp v240, v14, v160 row_shr:1 row_mask:0xf bank_mask:0xf
	v_fmac_f32_dpp v241, v15, v161 row_shr:1 row_mask:0xf bank_mask:0xf
	v_fmac_f32_dpp v238, v16, v158 row_shl:15 row_mask:0xf bank_mask:0xf
	v_fmac_f32_dpp v239, v17, v159 row_shl:15 row_mask:0xf bank_mask:0xf
	v_fmac_f32_dpp v240, v18, v160 row_shl:15 row_mask:0xf bank_mask:0xf
	v_fmac_f32_dpp v241, v19, v161 row_shl:15 row_mask:0xf bank_mask:0xf
	v_fmac_f32_dpp v238, v12, v166 row_shl:1 row_mask:0xf bank_mask:0xf
	v_fmac_f32_dpp v239, v13, v167 row_shl:1 row_mask:0xf bank_mask:0xf
	v_fmac_f32_dpp v240, v14, v168 row_shl:1 row_mask:0xf bank_mask:0xf
; __device__ __forceinline__ unsigned cvt_pk_bf16(float lo, float hi) { unsigned r; asm volatile("v_cvt_pk_bf16_f32 %0, %1, %2" : "=v"(r) : "v"(lo), "v"(hi)); return r; }
; #define PG8_BAR __builtin_amdgcn_s_barrier()
;     __device__ __forceinline__ void operator()(const f32x4 (&acc)[2][2][4][2], const Unit& u, int wr, int wc, int fr_in, int fq_in) const {
;     ...
;                             for (int j = 0; j < 4; ++j) e[j] = __builtin_amdgcn_rcpf(1.0f + __builtin_amdgcn_exp2f(c[j] * -1.4426950408889634f));
;                             o[m] = o[m] * (c * e); }
;                         up_prev = up_cur; dn_cur = dn_next; }
;                 }
;                 if (n == 0) {
; #pragma unroll
;                     for (int m = 0; m < 4; ++m) { wlo[m].x = cvt_pk_bf16(o[m][0], o[m][1]); wlo[m].y = cvt_pk_bf16(o[m][2], o[m][3]); }
;                 } else {
; #pragma unroll
;                     for (int m = 0; m < 4; ++m) { u32x4 w; w.x = wlo[m].x; w.y = wlo[m].y; w.z = cvt_pk_bf16(o[m][0], o[m][1]); w.w = cvt_pk_bf16(o[m][2], o[m][3]);
;                         *(u32x4*)(base + off0 + (unsigned)(ai * HALF + m * 16) * (DFF * 2u)) = w; }
; template <class Epi>
; __device__ __forceinline__ void gemm_phase(ldsp lds, const Gemm g, const StaticOrder& S, const Epi& E, const int tid) {
;     ...
;         if (wr == 0) PG8_BAR;
;         if constexpr (!Epi::AFTER_DRAIN) E(acc, cur, wr, wc, fr, fq);
;         if (!has_next) break;
; #pragma unroll
;         for (int a = 0; a < 2; ++a)
; #pragma unroll
;             for (int b = 0; b < 2; ++b)
; #pragma unroll
;                 for (int m = 0; m < 4; ++m)
; #pragma unroll
;                     for (int n = 0; n < 2; ++n) acc[a][b][m][n] = (f32x4){0.f, 0.f, 0.f, 0.f};
;         cur = nxt; cA = nA; cB = nB; ++ui;
;         if (wr == 1) PG8_BAR;
	v_fmac_f32_dpp v241, v15, v169 row_shl:1 row_mask:0xf bank_mask:0xf
	v_mul_f32_e32 v242, 0xbfb8aa3b, v226
	v_mul_f32_e32 v243, 0xbfb8aa3b, v227
	v_mul_f32_e32 v244, 0xbfb8aa3b, v228
	v_mul_f32_e32 v245, 0xbfb8aa3b, v229
	v_mul_f32_e32 v246, 0xbfb8aa3b, v230
	v_mul_f32_e32 v247, 0xbfb8aa3b, v231
	v_mul_f32_e32 v248, 0xbfb8aa3b, v232
	v_mul_f32_e32 v249, 0xbfb8aa3b, v233
	v_exp_f32_e32 v242, v242
	v_exp_f32_e32 v243, v243
	v_exp_f32_e32 v244, v244
	v_exp_f32_e32 v245, v245
	v_exp_f32_e32 v246, v246
	v_exp_f32_e32 v247, v247
	v_exp_f32_e32 v248, v248
	v_exp_f32_e32 v249, v249
	v_add_f32_e32 v242, 1.0, v242
	v_add_f32_e32 v243, 1.0, v243
	v_add_f32_e32 v244, 1.0, v244
	v_add_f32_e32 v245, 1.0, v245
	v_add_f32_e32 v246, 1.0, v246
	v_add_f32_e32 v247, 1.0, v247
	v_add_f32_e32 v248, 1.0, v248
	v_add_f32_e32 v249, 1.0, v249
	v_rcp_f32_e32 v242, v242
	v_rcp_f32_e32 v243, v243
	v_rcp_f32_e32 v244, v244
	v_rcp_f32_e32 v245, v245
	v_rcp_f32_e32 v246, v246
	v_rcp_f32_e32 v247, v247
	v_rcp_f32_e32 v248, v248
	v_rcp_f32_e32 v249, v249
	v_mul_f32_e32 v242, v226, v242
	v_mul_f32_e32 v243, v227, v243
	v_mul_f32_e32 v244, v228, v244
	v_mul_f32_e32 v245, v229, v245
	v_mul_f32_e32 v246, v230, v246
	v_mul_f32_e32 v247, v231, v247
	v_mul_f32_e32 v248, v232, v248
	v_mul_f32_e32 v249, v233, v249
	v_mul_f32_e32 v174, v174, v242
	v_mul_f32_e32 v175, v175, v243
	v_mul_f32_e32 v176, v176, v244
	v_mul_f32_e32 v177, v177, v245
	v_mul_f32_e32 v178, v178, v246
	v_mul_f32_e32 v179, v179, v247
	v_mul_f32_e32 v180, v180, v248
	v_mul_f32_e32 v181, v181, v249
	v_mul_f32_e32 v242, 0xbfb8aa3b, v234
	v_mul_f32_e32 v243, 0xbfb8aa3b, v235
	v_mul_f32_e32 v244, 0xbfb8aa3b, v236
	v_mul_f32_e32 v245, 0xbfb8aa3b, v237
	v_mul_f32_e32 v246, 0xbfb8aa3b, v238
	v_mul_f32_e32 v247, 0xbfb8aa3b, v239
	v_mul_f32_e32 v248, 0xbfb8aa3b, v240
	v_mul_f32_e32 v249, 0xbfb8aa3b, v241
	v_exp_f32_e32 v242, v242
	v_exp_f32_e32 v243, v243
	v_exp_f32_e32 v244, v244
	v_exp_f32_e32 v245, v245
	v_exp_f32_e32 v246, v246
	v_exp_f32_e32 v247, v247
	v_exp_f32_e32 v248, v248
	v_exp_f32_e32 v249, v249
	v_add_f32_e32 v242, 1.0, v242
	v_add_f32_e32 v243, 1.0, v243
	v_add_f32_e32 v244, 1.0, v244
	v_add_f32_e32 v245, 1.0, v245
	v_add_f32_e32 v246, 1.0, v246
	v_add_f32_e32 v247, 1.0, v247
	v_add_f32_e32 v248, 1.0, v248
	v_add_f32_e32 v249, 1.0, v249
	v_rcp_f32_e32 v242, v242
	v_rcp_f32_e32 v243, v243
	v_rcp_f32_e32 v244, v244
	v_rcp_f32_e32 v245, v245
	v_rcp_f32_e32 v246, v246
	v_rcp_f32_e32 v247, v247
	v_rcp_f32_e32 v248, v248
	v_rcp_f32_e32 v249, v249
	v_mul_f32_e32 v242, v234, v242
	v_mul_f32_e32 v243, v235, v243
	v_mul_f32_e32 v244, v236, v244
	v_mul_f32_e32 v245, v237, v245
	v_mul_f32_e32 v246, v238, v246
	v_mul_f32_e32 v247, v239, v247
	v_mul_f32_e32 v248, v240, v248
	v_mul_f32_e32 v249, v241, v249
	v_mul_f32_e32 v186, v186, v242
	v_mul_f32_e32 v187, v187, v243
	v_mul_f32_e32 v188, v188, v244
	v_mul_f32_e32 v189, v189, v245
	v_mul_f32_e32 v190, v190, v246
	v_mul_f32_e32 v191, v191, v247
	v_mul_f32_e32 v192, v192, v248
	v_mul_f32_e32 v193, v193, v249
	v_cvt_pk_bf16_f32 v46, v174, v175
	v_cvt_pk_bf16_f32 v47, v176, v177
	v_cvt_pk_bf16_f32 v62, v178, v179
	v_cvt_pk_bf16_f32 v63, v180, v181
	v_cvt_pk_bf16_f32 v58, v186, v187
	v_cvt_pk_bf16_f32 v59, v188, v189
	v_cvt_pk_bf16_f32 v42, v190, v191
	v_cvt_pk_bf16_f32 v43, v192, v193
	s_add_u32 s0, s6, 0xb0000
	s_addc_u32 s1, s7, 0
	global_store_dwordx4 v194, v[44:47], s[0:1]
	s_add_u32 s0, s6, 0xc6000
	s_addc_u32 s1, s7, 0
	global_store_dwordx4 v194, v[60:63], s[0:1]
	s_add_u32 s0, s6, 0xdc000
	s_addc_u32 s1, s7, 0
	global_store_dwordx4 v194, v[56:59], s[0:1]
	s_add_u32 s0, s6, 0xf2000
	s_addc_u32 s1, s7, 0
	global_store_dwordx4 v194, v[40:43], s[0:1]
	s_mov_b32 s101, 0
	s_cmp_eq_u64 s[4:5], 0
	s_cbranch_scc1 .Lp7_nopf
	v_and_b32_e32 v214, 63, v196
	v_bfe_u32 v130, v214, 2, 2
	v_bfe_u32 v131, v214, 4, 1
	v_lshrrev_b32_e32 v96, 5, v214
	v_and_b32_e32 v214, 3, v214
	s_lshl_b32 s0, s94, 7
	s_or_b32 s0, s0, s14
	v_lshl_add_u32 v214, v214, 3, s0
	v_lshl_add_u32 v214, v96, 2, v214
	v_lshlrev_b32_e32 v214, 2, v214
	v_mul_u32_u24_e32 v131, 0x2c00, v131
	v_add_u32_e32 v214, v214, v131
	v_cmp_eq_u32_e32 vcc, 3, v130
	v_mul_u32_u24_e32 v130, 0x5800, v130
	v_mov_b32_e32 v131, s53
	v_mov_b32_e32 v96, s54
	v_cndmask_b32_e64 v130, v130, 0, vcc
	v_add_u32_e32 v214, v214, v130
	v_mov_b32_e32 v130, s52
	v_cndmask_b32_e32 v130, v130, v96, vcc
	v_mov_b32_e32 v96, s55
	v_cndmask_b32_e32 v131, v131, v96, vcc
	v_add_co_u32_e32 v214, vcc, v130, v214
	s_nop 1
	v_addc_co_u32_e32 v215, vcc, 0, v131, vcc
	s_mov_b32 m0, s100
	s_nop 0
	global_load_lds_dwordx4 v[214:215], off
	s_movk_i32 s101, 0x7a9
.Lp7_nopf:
.LBB0_1054:
	s_or_b64 exec, exec, s[10:11]
	s_andn2_b64 vcc, exec, s[4:5]
	s_mov_b64 s[4:5], -1
	s_cbranch_vccnz .LBB0_1039
	v_readlane_b32 s0, v254, 49
	v_readlane_b32 s1, v254, 50
	s_andn2_b64 vcc, exec, s[0:1]
	s_cbranch_vccnz .LBB0_1038
	s_barrier
	s_branch .LBB0_1038
